# FFN-out GEMM K-loops (2 of 7): A rows 2,3 fragment reads hoisted next to rows 0,1 + B reads, MFMA sections paired (32 MFMAs between barriers), 8 instead of 16 workgroup barriers per iteration
# baseline (speedup 1.0000x reference)
.LBB0_117:
	v_bfe_u32 v17, v16, 4, 2
	v_and_b32_e32 v18, 15, v16
	v_lshlrev_b32_e32 v19, 4, v17
	v_lshlrev_b32_e32 v16, 2, v16
	v_lshl_or_b32 v142, s8, 6, v18
	v_lshl_or_b32 v18, v18, 6, v19
	s_lshl_b32 s8, s8, 13
	v_and_b32_e32 v16, 32, v16
	s_lshr_b32 s10, s10, 2
	v_bitop3_b32 v19, v18, s8, v16 bitop3:0xde
	s_lshl_b32 s8, s9, 5
	s_sext_i32_i8 s38, s10
	s_and_b32 s10, s8, 0x60
	s_add_i32 m0, s26, 0x18000
	v_lshl_add_u64 v[6:7], v[6:7], 0, s[6:7]
	s_lshl_b32 s8, s10, 7
	s_waitcnt vmcnt(0)
	s_barrier
	global_load_lds_dwordx4 v[6:7], off
	v_lshl_add_u64 v[4:5], v[4:5], 0, s[6:7]
	s_add_i32 m0, s26, 0x1a000
	s_add_i32 s30, s26, 0x8000
	s_add_i32 s31, s26, 0xa000
	v_bitop3_b32 v143, v18, s8, v16 bitop3:0xde
	global_load_lds_dwordx4 v[4:5], off
	v_lshl_add_u64 v[2:3], v[2:3], 0, s[6:7]
	s_mov_b32 m0, s30
	s_add_u32 s8, s16, 0x160080
	global_load_lds_dwordx4 v[2:3], off
	v_lshl_add_u64 v[0:1], v[0:1], 0, s[6:7]
	s_mov_b32 m0, s31
	s_addc_u32 s9, s17, 0
	global_load_lds_dwordx4 v[0:1], off
	s_add_i32 m0, s26, 0x1c000
	v_lshl_add_u64 v[0:1], s[8:9], 0, v[128:129]
	global_load_lds_dwordx4 v[0:1], off
	v_lshl_add_u64 v[0:1], s[8:9], 0, v[130:131]
	s_add_i32 m0, s26, 0x1e000
	s_movk_i32 s11, 0x1600
	global_load_lds_dwordx4 v[0:1], off
	v_lshl_or_b32 v144, v17, 2, s10
	v_lshrrev_b32_e32 v1, 1, v8
	v_mul_lo_u32 v0, v10, s11
	s_mov_b32 s10, 0x16000
	v_mad_u64_u32 v[0:1], s[8:9], v1, s10, v[0:1]
	v_or_b32_e32 v0, v0, v9
	v_add_lshl_u32 v0, v0, v11, 1
	v_mov_b32_e32 v1, v129
	s_mov_b64 s[12:13], 0x160080
	v_lshl_add_u64 v[132:133], v[0:1], 0, s[12:13]
	v_lshrrev_b32_e32 v1, 1, v12
	v_mul_lo_u32 v0, v14, s11
	v_mad_u64_u32 v[0:1], s[8:9], v1, s10, v[0:1]
	s_waitcnt vmcnt(6)
	v_or_b32_e32 v0, v0, v13
	v_add_lshl_u32 v0, v0, v15, 1
	v_mov_b32_e32 v1, v129
	v_lshl_add_u64 v[134:135], v[0:1], 0, s[12:13]
	s_mov_b32 s34, 0
	v_add_u32_e32 v145, 0, v19
	s_barrier

.LBB0_129:
	s_add_u32 s16, s14, 0x100
	s_addc_u32 s17, s15, 0
	s_add_i32 s42, 0, 0x10000
	v_add_u32_e32 v140, s42, v143
	ds_read_b128 v[136:139], v140
	ds_read_b128 v[146:149], v140 offset:1024
	ds_read_b128 v[150:153], v140 offset:2048
	ds_read_b128 v[154:157], v140 offset:3072
	s_cmpk_eq_i32 s41, 0x54
	s_cselect_b32 s21, s11, s17
	s_cselect_b32 s20, s10, s16
	s_cselect_b32 s19, s13, s40
	s_cselect_b32 s18, s12, s39
	v_lshl_add_u64 v[140:141], s[14:15], 0, v[132:133]
	s_add_i32 m0, s26, 0xc000
	ds_read_b128 v[158:161], v145
	ds_read_b128 v[176:179], v145 offset:1024
	ds_read_b128 v[180:183], v145 offset:2048
	ds_read_b128 v[184:187], v145 offset:3072
	ds_read_b128 v[188:191], v145 offset:4096
	ds_read_b128 v[192:195], v145 offset:5120
	ds_read_b128 v[208:211], v145 offset:6144
	ds_read_b128 v[212:215], v145 offset:7168
	global_load_lds_dwordx4 v[140:141], off
	v_lshl_add_u64 v[140:141], s[14:15], 0, v[134:135]
	s_add_i32 m0, s26, 0xe000
	s_nop 0
	global_load_lds_dwordx4 v[140:141], off
	s_waitcnt lgkmcnt(8)
	s_add_i32 s43, 0, 0x14000
	v_add_u32_e32 v196, s43, v143
	ds_read_b128 v[216:219], v196
	ds_read_b128 v[220:223], v196 offset:1024
	ds_read_b128 v[224:227], v196 offset:2048
	ds_read_b128 v[228:231], v196 offset:3072
	s_barrier
	s_waitcnt lgkmcnt(0)
	s_setprio 1
	s_waitcnt lgkmcnt(0)
	v_mfma_f32_16x16x32_bf16 v[124:127], v[136:139], v[158:161], v[124:127]
	v_mfma_f32_16x16x32_bf16 v[120:123], v[150:153], v[158:161], v[120:123]
	v_mfma_f32_16x16x32_bf16 v[108:111], v[136:139], v[180:183], v[108:111]
	v_mfma_f32_16x16x32_bf16 v[104:107], v[150:153], v[180:183], v[104:107]
	v_mfma_f32_16x16x32_bf16 v[92:95], v[136:139], v[188:191], v[92:95]
	v_mfma_f32_16x16x32_bf16 v[88:91], v[150:153], v[188:191], v[88:91]
	v_mfma_f32_16x16x32_bf16 v[76:79], v[136:139], v[208:211], v[76:79]
	v_mfma_f32_16x16x32_bf16 v[72:75], v[150:153], v[208:211], v[72:75]
	v_mfma_f32_16x16x32_bf16 v[124:127], v[146:149], v[176:179], v[124:127]
	v_mfma_f32_16x16x32_bf16 v[120:123], v[154:157], v[176:179], v[120:123]
	v_mfma_f32_16x16x32_bf16 v[108:111], v[146:149], v[184:187], v[108:111]
	v_mfma_f32_16x16x32_bf16 v[104:107], v[154:157], v[184:187], v[104:107]
	v_mfma_f32_16x16x32_bf16 v[92:95], v[146:149], v[192:195], v[92:95]
	v_mfma_f32_16x16x32_bf16 v[88:91], v[154:157], v[192:195], v[88:91]
	v_mfma_f32_16x16x32_bf16 v[76:79], v[146:149], v[212:215], v[76:79]
	v_mfma_f32_16x16x32_bf16 v[72:75], v[154:157], v[212:215], v[72:75]
	s_setprio 0
	s_waitcnt lgkmcnt(0)
	s_setprio 1
	s_waitcnt lgkmcnt(0)
	v_mfma_f32_16x16x32_bf16 v[116:119], v[216:219], v[158:161], v[116:119]
	v_mfma_f32_16x16x32_bf16 v[112:115], v[224:227], v[158:161], v[112:115]
	v_mfma_f32_16x16x32_bf16 v[100:103], v[216:219], v[180:183], v[100:103]
	v_mfma_f32_16x16x32_bf16 v[96:99], v[224:227], v[180:183], v[96:99]
	v_mfma_f32_16x16x32_bf16 v[84:87], v[216:219], v[188:191], v[84:87]
	v_mfma_f32_16x16x32_bf16 v[80:83], v[224:227], v[188:191], v[80:83]
	v_mfma_f32_16x16x32_bf16 v[68:71], v[216:219], v[208:211], v[68:71]
	v_mfma_f32_16x16x32_bf16 v[64:67], v[224:227], v[208:211], v[64:67]
	v_mfma_f32_16x16x32_bf16 v[116:119], v[220:223], v[176:179], v[116:119]
	v_mfma_f32_16x16x32_bf16 v[112:115], v[228:231], v[176:179], v[112:115]
	v_mfma_f32_16x16x32_bf16 v[100:103], v[220:223], v[184:187], v[100:103]
	v_mfma_f32_16x16x32_bf16 v[96:99], v[228:231], v[184:187], v[96:99]
	v_mfma_f32_16x16x32_bf16 v[84:87], v[220:223], v[192:195], v[84:87]
	v_mfma_f32_16x16x32_bf16 v[80:83], v[228:231], v[192:195], v[80:83]
	v_mfma_f32_16x16x32_bf16 v[68:71], v[220:223], v[212:215], v[68:71]
	v_mfma_f32_16x16x32_bf16 v[64:67], v[228:231], v[212:215], v[64:67]
	s_setprio 0
	s_barrier
	s_add_i32 s14, s42, s25
	v_lshl_add_u64 v[140:141], s[18:19], 0, v[128:129]
	s_mov_b32 m0, s14
	v_lshl_add_u64 v[232:233], s[18:19], 0, v[130:131]
	global_load_lds_dwordx4 v[140:141], off
	s_add_i32 m0, s14, 0x2000
	s_nop 0
	global_load_lds_dwordx4 v[232:233], off
	s_mov_b32 m0, s26
	v_lshl_add_u64 v[234:235], s[20:21], 0, v[128:129]
	ds_read_b128 v[158:161], v145 offset:16384
	ds_read_b128 v[176:179], v145 offset:17408
	ds_read_b128 v[180:183], v145 offset:18432
	ds_read_b128 v[184:187], v145 offset:19456
	ds_read_b128 v[188:191], v145 offset:20480
	ds_read_b128 v[192:195], v145 offset:21504
	ds_read_b128 v[208:211], v145 offset:22528
	ds_read_b128 v[212:215], v145 offset:23552
	global_load_lds_dwordx4 v[234:235], off
	v_lshl_add_u64 v[236:237], s[20:21], 0, v[130:131]
	s_mov_b32 m0, s27
	s_nop 0
	global_load_lds_dwordx4 v[236:237], off
	s_waitcnt vmcnt(4)
	s_barrier
	s_waitcnt lgkmcnt(0)
	s_setprio 1
	s_waitcnt lgkmcnt(0)
	v_mfma_f32_16x16x32_bf16 v[60:63], v[136:139], v[158:161], v[60:63]
	v_mfma_f32_16x16x32_bf16 v[56:59], v[150:153], v[158:161], v[56:59]
	v_mfma_f32_16x16x32_bf16 v[44:47], v[136:139], v[180:183], v[44:47]
	v_mfma_f32_16x16x32_bf16 v[40:43], v[150:153], v[180:183], v[40:43]
	v_mfma_f32_16x16x32_bf16 v[28:31], v[136:139], v[188:191], v[28:31]
	v_mfma_f32_16x16x32_bf16 v[24:27], v[150:153], v[188:191], v[24:27]
	v_mfma_f32_16x16x32_bf16 v[12:15], v[136:139], v[208:211], v[12:15]
	v_mfma_f32_16x16x32_bf16 v[8:11], v[150:153], v[208:211], v[8:11]
	v_mfma_f32_16x16x32_bf16 v[60:63], v[146:149], v[176:179], v[60:63]
	v_mfma_f32_16x16x32_bf16 v[56:59], v[154:157], v[176:179], v[56:59]
	v_mfma_f32_16x16x32_bf16 v[44:47], v[146:149], v[184:187], v[44:47]
	v_mfma_f32_16x16x32_bf16 v[40:43], v[154:157], v[184:187], v[40:43]
	v_mfma_f32_16x16x32_bf16 v[28:31], v[146:149], v[192:195], v[28:31]
	v_mfma_f32_16x16x32_bf16 v[24:27], v[154:157], v[192:195], v[24:27]
	v_mfma_f32_16x16x32_bf16 v[12:15], v[146:149], v[212:215], v[12:15]
	v_mfma_f32_16x16x32_bf16 v[8:11], v[154:157], v[212:215], v[8:11]
	s_setprio 0
	s_add_u32 s14, s18, 0x160000
	s_addc_u32 s15, s19, 0
	s_add_i32 s42, s43, s25
	v_lshl_add_u64 v[136:137], s[14:15], 0, v[128:129]
	s_mov_b32 m0, s42
	s_nop 0
	global_load_lds_dwordx4 v[136:137], off
	v_lshl_add_u64 v[136:137], s[14:15], 0, v[130:131]
	s_add_i32 m0, s42, 0x2000
	s_nop 0
	global_load_lds_dwordx4 v[136:137], off
	s_setprio 1
	v_mfma_f32_16x16x32_bf16 v[52:55], v[216:219], v[158:161], v[52:55]
	v_mfma_f32_16x16x32_bf16 v[48:51], v[224:227], v[158:161], v[48:51]
	v_mfma_f32_16x16x32_bf16 v[36:39], v[216:219], v[180:183], v[36:39]
	v_mfma_f32_16x16x32_bf16 v[32:35], v[224:227], v[180:183], v[32:35]
	v_mfma_f32_16x16x32_bf16 v[20:23], v[216:219], v[188:191], v[20:23]
	v_mfma_f32_16x16x32_bf16 v[16:19], v[224:227], v[188:191], v[16:19]
	v_mfma_f32_16x16x32_bf16 v[4:7], v[216:219], v[208:211], v[4:7]
	v_mfma_f32_16x16x32_bf16 v[0:3], v[224:227], v[208:211], v[0:3]
	v_mfma_f32_16x16x32_bf16 v[52:55], v[220:223], v[176:179], v[52:55]
	v_mfma_f32_16x16x32_bf16 v[48:51], v[228:231], v[176:179], v[48:51]
	v_mfma_f32_16x16x32_bf16 v[36:39], v[220:223], v[184:187], v[36:39]
	v_mfma_f32_16x16x32_bf16 v[32:35], v[228:231], v[184:187], v[32:35]
	v_mfma_f32_16x16x32_bf16 v[20:23], v[220:223], v[192:195], v[20:23]
	v_mfma_f32_16x16x32_bf16 v[16:19], v[228:231], v[192:195], v[16:19]
	v_mfma_f32_16x16x32_bf16 v[4:7], v[220:223], v[212:215], v[4:7]
	v_mfma_f32_16x16x32_bf16 v[0:3], v[228:231], v[212:215], v[0:3]
	s_setprio 0
	s_add_i32 s42, 0, 0x18000
	v_add_u32_e32 v154, s42, v143
	s_barrier
	ds_read_b128 v[136:139], v154
	ds_read_b128 v[146:149], v154 offset:1024
	ds_read_b128 v[150:153], v154 offset:2048
	ds_read_b128 v[154:157], v154 offset:3072
	s_add_u32 s14, s20, 0x160000
	s_addc_u32 s15, s21, 0
	s_mov_b32 m0, s28
	v_lshl_add_u64 v[216:217], s[14:15], 0, v[128:129]
	ds_read_b128 v[158:161], v145 offset:32768
	ds_read_b128 v[176:179], v145 offset:33792
	ds_read_b128 v[180:183], v145 offset:34816
	ds_read_b128 v[184:187], v145 offset:35840
	ds_read_b128 v[188:191], v145 offset:36864
	ds_read_b128 v[192:195], v145 offset:37888
	ds_read_b128 v[208:211], v145 offset:38912
	ds_read_b128 v[212:215], v145 offset:39936
	global_load_lds_dwordx4 v[216:217], off
	v_lshl_add_u64 v[216:217], s[14:15], 0, v[130:131]
	s_mov_b32 m0, s29
	s_nop 0
	global_load_lds_dwordx4 v[216:217], off
	s_waitcnt lgkmcnt(8)
	s_add_i32 s20, 0, 0x1c000
	v_add_u32_e32 v196, s20, v143
	ds_read_b128 v[216:219], v196
	ds_read_b128 v[220:223], v196 offset:1024
	ds_read_b128 v[224:227], v196 offset:2048
	ds_read_b128 v[228:231], v196 offset:3072
	s_barrier
	s_waitcnt lgkmcnt(0)
	s_setprio 1
	s_waitcnt lgkmcnt(0)
	v_mfma_f32_16x16x32_bf16 v[124:127], v[136:139], v[158:161], v[124:127]
	v_mfma_f32_16x16x32_bf16 v[120:123], v[150:153], v[158:161], v[120:123]
	v_mfma_f32_16x16x32_bf16 v[108:111], v[136:139], v[180:183], v[108:111]
	v_mfma_f32_16x16x32_bf16 v[104:107], v[150:153], v[180:183], v[104:107]
	v_mfma_f32_16x16x32_bf16 v[92:95], v[136:139], v[188:191], v[92:95]
	v_mfma_f32_16x16x32_bf16 v[88:91], v[150:153], v[188:191], v[88:91]
	v_mfma_f32_16x16x32_bf16 v[76:79], v[136:139], v[208:211], v[76:79]
	v_mfma_f32_16x16x32_bf16 v[72:75], v[150:153], v[208:211], v[72:75]
	v_mfma_f32_16x16x32_bf16 v[124:127], v[146:149], v[176:179], v[124:127]
	v_mfma_f32_16x16x32_bf16 v[120:123], v[154:157], v[176:179], v[120:123]
	v_mfma_f32_16x16x32_bf16 v[108:111], v[146:149], v[184:187], v[108:111]
	v_mfma_f32_16x16x32_bf16 v[104:107], v[154:157], v[184:187], v[104:107]
	v_mfma_f32_16x16x32_bf16 v[92:95], v[146:149], v[192:195], v[92:95]
	v_mfma_f32_16x16x32_bf16 v[88:91], v[154:157], v[192:195], v[88:91]
	v_mfma_f32_16x16x32_bf16 v[76:79], v[146:149], v[212:215], v[76:79]
	v_mfma_f32_16x16x32_bf16 v[72:75], v[154:157], v[212:215], v[72:75]
	s_setprio 0
	s_waitcnt lgkmcnt(0)
	s_setprio 1
	s_waitcnt lgkmcnt(0)
	v_mfma_f32_16x16x32_bf16 v[116:119], v[216:219], v[158:161], v[116:119]
	v_mfma_f32_16x16x32_bf16 v[112:115], v[224:227], v[158:161], v[112:115]
	v_mfma_f32_16x16x32_bf16 v[100:103], v[216:219], v[180:183], v[100:103]
	v_mfma_f32_16x16x32_bf16 v[96:99], v[224:227], v[180:183], v[96:99]
	v_mfma_f32_16x16x32_bf16 v[84:87], v[216:219], v[188:191], v[84:87]
	v_mfma_f32_16x16x32_bf16 v[80:83], v[224:227], v[188:191], v[80:83]
	v_mfma_f32_16x16x32_bf16 v[68:71], v[216:219], v[208:211], v[68:71]
	v_mfma_f32_16x16x32_bf16 v[64:67], v[224:227], v[208:211], v[64:67]
	v_mfma_f32_16x16x32_bf16 v[116:119], v[220:223], v[176:179], v[116:119]
	v_mfma_f32_16x16x32_bf16 v[112:115], v[228:231], v[176:179], v[112:115]
	v_mfma_f32_16x16x32_bf16 v[100:103], v[220:223], v[184:187], v[100:103]
	v_mfma_f32_16x16x32_bf16 v[96:99], v[228:231], v[184:187], v[96:99]
	v_mfma_f32_16x16x32_bf16 v[84:87], v[220:223], v[192:195], v[84:87]
	v_mfma_f32_16x16x32_bf16 v[80:83], v[228:231], v[192:195], v[80:83]
	v_mfma_f32_16x16x32_bf16 v[68:71], v[220:223], v[212:215], v[68:71]
	v_mfma_f32_16x16x32_bf16 v[64:67], v[228:231], v[212:215], v[64:67]
	s_setprio 0
	s_barrier
	s_add_i32 s14, s42, s25
	v_lshl_add_u64 v[140:141], v[140:141], 0, s[6:7]
	s_mov_b32 m0, s14
	global_load_lds_dwordx4 v[140:141], off
	v_lshl_add_u64 v[140:141], v[232:233], 0, s[6:7]
	s_add_i32 m0, s14, 0x2000
	s_nop 0
	global_load_lds_dwordx4 v[140:141], off
	s_mov_b32 m0, s30
	v_lshl_add_u64 v[140:141], v[234:235], 0, s[6:7]
	ds_read_b128 v[158:161], v145 offset:49152
	ds_read_b128 v[176:179], v145 offset:50176
	ds_read_b128 v[180:183], v145 offset:51200
	ds_read_b128 v[184:187], v145 offset:52224
	ds_read_b128 v[188:191], v145 offset:53248
	ds_read_b128 v[192:195], v145 offset:54272
	ds_read_b128 v[208:211], v145 offset:55296
	ds_read_b128 v[212:215], v145 offset:56320
	global_load_lds_dwordx4 v[140:141], off
	v_lshl_add_u64 v[140:141], v[236:237], 0, s[6:7]
	s_mov_b32 m0, s31
	s_nop 0
	global_load_lds_dwordx4 v[140:141], off
	s_waitcnt vmcnt(4)
	s_barrier
	s_waitcnt lgkmcnt(0)
	s_setprio 1
	s_waitcnt lgkmcnt(0)
	v_mfma_f32_16x16x32_bf16 v[60:63], v[136:139], v[158:161], v[60:63]
	v_mfma_f32_16x16x32_bf16 v[56:59], v[150:153], v[158:161], v[56:59]
	v_mfma_f32_16x16x32_bf16 v[44:47], v[136:139], v[180:183], v[44:47]
	v_mfma_f32_16x16x32_bf16 v[40:43], v[150:153], v[180:183], v[40:43]
	v_mfma_f32_16x16x32_bf16 v[28:31], v[136:139], v[188:191], v[28:31]
	v_mfma_f32_16x16x32_bf16 v[24:27], v[150:153], v[188:191], v[24:27]
	v_mfma_f32_16x16x32_bf16 v[12:15], v[136:139], v[208:211], v[12:15]
	v_mfma_f32_16x16x32_bf16 v[8:11], v[150:153], v[208:211], v[8:11]
	v_mfma_f32_16x16x32_bf16 v[60:63], v[146:149], v[176:179], v[60:63]
	v_mfma_f32_16x16x32_bf16 v[56:59], v[154:157], v[176:179], v[56:59]
	v_mfma_f32_16x16x32_bf16 v[44:47], v[146:149], v[184:187], v[44:47]
	v_mfma_f32_16x16x32_bf16 v[40:43], v[154:157], v[184:187], v[40:43]
	v_mfma_f32_16x16x32_bf16 v[28:31], v[146:149], v[192:195], v[28:31]
	v_mfma_f32_16x16x32_bf16 v[24:27], v[154:157], v[192:195], v[24:27]
	v_mfma_f32_16x16x32_bf16 v[12:15], v[146:149], v[212:215], v[12:15]
	v_mfma_f32_16x16x32_bf16 v[8:11], v[154:157], v[212:215], v[8:11]
	s_setprio 0
	s_add_u32 s14, s18, 0x160080
	s_addc_u32 s15, s19, 0
	s_add_i32 s18, s20, s25
	v_lshl_add_u64 v[136:137], s[14:15], 0, v[128:129]
	s_mov_b32 m0, s18
	s_nop 0
	global_load_lds_dwordx4 v[136:137], off
	v_lshl_add_u64 v[136:137], s[14:15], 0, v[130:131]
	s_add_i32 m0, s18, 0x2000
	s_nop 0
	global_load_lds_dwordx4 v[136:137], off
	s_setprio 1
	v_mfma_f32_16x16x32_bf16 v[52:55], v[216:219], v[158:161], v[52:55]
	v_mfma_f32_16x16x32_bf16 v[48:51], v[224:227], v[158:161], v[48:51]
	v_mfma_f32_16x16x32_bf16 v[36:39], v[216:219], v[180:183], v[36:39]
	v_mfma_f32_16x16x32_bf16 v[32:35], v[224:227], v[180:183], v[32:35]
	v_mfma_f32_16x16x32_bf16 v[20:23], v[216:219], v[188:191], v[20:23]
	v_mfma_f32_16x16x32_bf16 v[16:19], v[224:227], v[188:191], v[16:19]
	v_mfma_f32_16x16x32_bf16 v[4:7], v[216:219], v[208:211], v[4:7]
	v_mfma_f32_16x16x32_bf16 v[0:3], v[224:227], v[208:211], v[0:3]
	v_mfma_f32_16x16x32_bf16 v[52:55], v[220:223], v[176:179], v[52:55]
	v_mfma_f32_16x16x32_bf16 v[48:51], v[228:231], v[176:179], v[48:51]
	v_mfma_f32_16x16x32_bf16 v[36:39], v[220:223], v[184:187], v[36:39]
	v_mfma_f32_16x16x32_bf16 v[32:35], v[228:231], v[184:187], v[32:35]
	v_mfma_f32_16x16x32_bf16 v[20:23], v[220:223], v[192:195], v[20:23]
	v_mfma_f32_16x16x32_bf16 v[16:19], v[228:231], v[192:195], v[16:19]
	v_mfma_f32_16x16x32_bf16 v[4:7], v[220:223], v[212:215], v[4:7]
	v_mfma_f32_16x16x32_bf16 v[0:3], v[228:231], v[212:215], v[0:3]
	s_setprio 0
	s_add_i32 s41, s41, 2
	s_add_u32 s39, s39, 0x100
	s_addc_u32 s40, s40, 0
	s_cmpk_gt_u32 s41, 0x55
	s_mov_b64 s[14:15], s[16:17]
	s_barrier
	s_cbranch_scc0 .LBB0_129
	v_lshl_add_u32 v136, s37, 8, v142
	v_lshl_or_b32 v137, s38, 8, v144
	v_lshl_add_u32 v137, v136, 11, v137
	v_lshlrev_b32_e32 v138, 1, v137
	v_lshlrev_b32_e32 v139, 2, v137
	s_mov_b32 s38, s35
	s_mov_b32 s37, s36
	v_readlane_b32 s14, v255, 34
	v_readlane_b32 s15, v255, 35
	s_nop 4
	s_mov_b64 s[16:17], s[76:77]
	global_load_dwordx2 v[148:149], v138, s[14:15] offset:0
	global_load_dwordx2 v[150:151], v138, s[14:15] offset:32
	global_load_dwordx2 v[152:153], v138, s[14:15] offset:256
	global_load_dwordx2 v[154:155], v138, s[14:15] offset:288
	s_add_u32 s14, s14, 0x10000
	s_addc_u32 s15, s15, 0
	global_load_dwordx2 v[156:157], v138, s[14:15] offset:0
	global_load_dwordx2 v[158:159], v138, s[14:15] offset:32
	global_load_dwordx2 v[160:161], v138, s[14:15] offset:256
	global_load_dwordx2 v[176:177], v138, s[14:15] offset:288
	s_add_u32 s14, s14, 0x10000
	s_addc_u32 s15, s15, 0
	global_load_dwordx2 v[178:179], v138, s[14:15] offset:0
	global_load_dwordx2 v[180:181], v138, s[14:15] offset:32
	global_load_dwordx2 v[182:183], v138, s[14:15] offset:256
	global_load_dwordx2 v[184:185], v138, s[14:15] offset:288
	s_add_u32 s14, s14, 0x10000
	s_addc_u32 s15, s15, 0
	global_load_dwordx2 v[186:187], v138, s[14:15] offset:0
	global_load_dwordx2 v[188:189], v138, s[14:15] offset:32
	global_load_dwordx2 v[190:191], v138, s[14:15] offset:256
	global_load_dwordx2 v[192:193], v138, s[14:15] offset:288
	s_add_u32 s14, s14, 0x50000
	s_addc_u32 s15, s15, 0
	global_load_dwordx2 v[194:195], v138, s[14:15] offset:0
	global_load_dwordx2 v[208:209], v138, s[14:15] offset:32
	global_load_dwordx2 v[210:211], v138, s[14:15] offset:256
	global_load_dwordx2 v[212:213], v138, s[14:15] offset:288
	s_add_u32 s14, s14, 0x10000
	s_addc_u32 s15, s15, 0
	global_load_dwordx2 v[214:215], v138, s[14:15] offset:0
	global_load_dwordx2 v[216:217], v138, s[14:15] offset:32
	global_load_dwordx2 v[218:219], v138, s[14:15] offset:256
	global_load_dwordx2 v[220:221], v138, s[14:15] offset:288
	s_add_u32 s14, s14, 0x10000
	s_addc_u32 s15, s15, 0
	global_load_dwordx2 v[222:223], v138, s[14:15] offset:0
	global_load_dwordx2 v[224:225], v138, s[14:15] offset:32
	global_load_dwordx2 v[226:227], v138, s[14:15] offset:256
	global_load_dwordx2 v[228:229], v138, s[14:15] offset:288
	s_add_u32 s14, s14, 0x10000
	s_addc_u32 s15, s15, 0
	global_load_dwordx2 v[230:231], v138, s[14:15] offset:0
	s_waitcnt vmcnt(28)
	v_lshlrev_b32_e32 v146, 16, v148
	v_and_b32_e32 v147, 0xffff0000, v148
	v_lshlrev_b32_e32 v148, 16, v149
	v_and_b32_e32 v149, 0xffff0000, v149
	v_pk_mul_f32 v[146:147], v[146:147], s[74:75] op_sel_hi:[1,0]
	v_pk_mul_f32 v[148:149], v[148:149], s[74:75] op_sel_hi:[1,0]
	v_pk_fma_f32 v[124:125], v[124:125], 0.5, v[146:147] op_sel_hi:[1,0,1]
	v_pk_fma_f32 v[126:127], v[126:127], 0.5, v[148:149] op_sel_hi:[1,0,1]
	global_store_dwordx4 v139, v[124:127], s[16:17] offset:0
	global_load_dwordx2 v[148:149], v138, s[14:15] offset:32
	s_waitcnt vmcnt(29)
	v_lshlrev_b32_e32 v146, 16, v150
	v_and_b32_e32 v147, 0xffff0000, v150
	v_lshlrev_b32_e32 v150, 16, v151
	v_and_b32_e32 v151, 0xffff0000, v151
	v_pk_mul_f32 v[146:147], v[146:147], s[74:75] op_sel_hi:[1,0]
	v_pk_mul_f32 v[150:151], v[150:151], s[74:75] op_sel_hi:[1,0]
	v_pk_fma_f32 v[120:121], v[120:121], 0.5, v[146:147] op_sel_hi:[1,0,1]
	v_pk_fma_f32 v[122:123], v[122:123], 0.5, v[150:151] op_sel_hi:[1,0,1]
	global_store_dwordx4 v139, v[120:123], s[16:17] offset:64
	global_load_dwordx2 v[150:151], v138, s[14:15] offset:256
	s_waitcnt vmcnt(30)
	v_lshlrev_b32_e32 v146, 16, v152
	v_and_b32_e32 v147, 0xffff0000, v152
	v_lshlrev_b32_e32 v152, 16, v153
	v_and_b32_e32 v153, 0xffff0000, v153
	v_pk_mul_f32 v[146:147], v[146:147], s[74:75] op_sel_hi:[1,0]
	v_pk_mul_f32 v[152:153], v[152:153], s[74:75] op_sel_hi:[1,0]
	v_pk_fma_f32 v[116:117], v[116:117], 0.5, v[146:147] op_sel_hi:[1,0,1]
	v_pk_fma_f32 v[118:119], v[118:119], 0.5, v[152:153] op_sel_hi:[1,0,1]
	global_store_dwordx4 v139, v[116:119], s[16:17] offset:512
	global_load_dwordx2 v[152:153], v138, s[14:15] offset:288
	s_waitcnt vmcnt(31)
	v_lshlrev_b32_e32 v146, 16, v154
	v_and_b32_e32 v147, 0xffff0000, v154
	v_lshlrev_b32_e32 v154, 16, v155
	v_and_b32_e32 v155, 0xffff0000, v155
	v_pk_mul_f32 v[146:147], v[146:147], s[74:75] op_sel_hi:[1,0]
	v_pk_mul_f32 v[154:155], v[154:155], s[74:75] op_sel_hi:[1,0]
	v_pk_fma_f32 v[112:113], v[112:113], 0.5, v[146:147] op_sel_hi:[1,0,1]
	v_pk_fma_f32 v[114:115], v[114:115], 0.5, v[154:155] op_sel_hi:[1,0,1]
	global_store_dwordx4 v139, v[112:115], s[16:17] offset:576
	s_waitcnt vmcnt(31)
	v_lshlrev_b32_e32 v146, 16, v156
	v_and_b32_e32 v147, 0xffff0000, v156
	v_lshlrev_b32_e32 v156, 16, v157
	v_and_b32_e32 v157, 0xffff0000, v157
	v_pk_mul_f32 v[146:147], v[146:147], s[74:75] op_sel_hi:[1,0]
	v_pk_mul_f32 v[156:157], v[156:157], s[74:75] op_sel_hi:[1,0]
	v_pk_fma_f32 v[108:109], v[108:109], 0.5, v[146:147] op_sel_hi:[1,0,1]
	v_pk_fma_f32 v[110:111], v[110:111], 0.5, v[156:157] op_sel_hi:[1,0,1]
	s_add_u32 s16, s16, 0x20000
	s_addc_u32 s17, s17, 0
	global_store_dwordx4 v139, v[108:111], s[16:17] offset:0
	s_waitcnt vmcnt(31)
	v_lshlrev_b32_e32 v146, 16, v158
	v_and_b32_e32 v147, 0xffff0000, v158
	v_lshlrev_b32_e32 v158, 16, v159
	v_and_b32_e32 v159, 0xffff0000, v159
	v_pk_mul_f32 v[146:147], v[146:147], s[74:75] op_sel_hi:[1,0]
	v_pk_mul_f32 v[158:159], v[158:159], s[74:75] op_sel_hi:[1,0]
	v_pk_fma_f32 v[104:105], v[104:105], 0.5, v[146:147] op_sel_hi:[1,0,1]
	v_pk_fma_f32 v[106:107], v[106:107], 0.5, v[158:159] op_sel_hi:[1,0,1]
	global_store_dwordx4 v139, v[104:107], s[16:17] offset:64
	s_waitcnt vmcnt(31)
	v_lshlrev_b32_e32 v146, 16, v160
	v_and_b32_e32 v147, 0xffff0000, v160
	v_lshlrev_b32_e32 v160, 16, v161
	v_and_b32_e32 v161, 0xffff0000, v161
	v_pk_mul_f32 v[146:147], v[146:147], s[74:75] op_sel_hi:[1,0]
	v_pk_mul_f32 v[160:161], v[160:161], s[74:75] op_sel_hi:[1,0]
	v_pk_fma_f32 v[100:101], v[100:101], 0.5, v[146:147] op_sel_hi:[1,0,1]
	v_pk_fma_f32 v[102:103], v[102:103], 0.5, v[160:161] op_sel_hi:[1,0,1]
	global_store_dwordx4 v139, v[100:103], s[16:17] offset:512
	s_waitcnt vmcnt(31)
	v_lshlrev_b32_e32 v146, 16, v176
	v_and_b32_e32 v147, 0xffff0000, v176
	v_lshlrev_b32_e32 v176, 16, v177
	v_and_b32_e32 v177, 0xffff0000, v177
	v_pk_mul_f32 v[146:147], v[146:147], s[74:75] op_sel_hi:[1,0]
	v_pk_mul_f32 v[176:177], v[176:177], s[74:75] op_sel_hi:[1,0]
	v_pk_fma_f32 v[96:97], v[96:97], 0.5, v[146:147] op_sel_hi:[1,0,1]
	v_pk_fma_f32 v[98:99], v[98:99], 0.5, v[176:177] op_sel_hi:[1,0,1]
	global_store_dwordx4 v139, v[96:99], s[16:17] offset:576
	s_waitcnt vmcnt(31)
	v_lshlrev_b32_e32 v146, 16, v178
	v_and_b32_e32 v147, 0xffff0000, v178
	v_lshlrev_b32_e32 v178, 16, v179
	v_and_b32_e32 v179, 0xffff0000, v179
	v_pk_mul_f32 v[146:147], v[146:147], s[74:75] op_sel_hi:[1,0]
	v_pk_mul_f32 v[178:179], v[178:179], s[74:75] op_sel_hi:[1,0]
	v_pk_fma_f32 v[92:93], v[92:93], 0.5, v[146:147] op_sel_hi:[1,0,1]
	v_pk_fma_f32 v[94:95], v[94:95], 0.5, v[178:179] op_sel_hi:[1,0,1]
	s_add_u32 s16, s16, 0x20000
	s_addc_u32 s17, s17, 0
	global_store_dwordx4 v139, v[92:95], s[16:17] offset:0
	s_waitcnt vmcnt(31)
	v_lshlrev_b32_e32 v146, 16, v180
	v_and_b32_e32 v147, 0xffff0000, v180
	v_lshlrev_b32_e32 v180, 16, v181
	v_and_b32_e32 v181, 0xffff0000, v181
	v_pk_mul_f32 v[146:147], v[146:147], s[74:75] op_sel_hi:[1,0]
	v_pk_mul_f32 v[180:181], v[180:181], s[74:75] op_sel_hi:[1,0]
	v_pk_fma_f32 v[88:89], v[88:89], 0.5, v[146:147] op_sel_hi:[1,0,1]
	v_pk_fma_f32 v[90:91], v[90:91], 0.5, v[180:181] op_sel_hi:[1,0,1]
	global_store_dwordx4 v139, v[88:91], s[16:17] offset:64
	s_waitcnt vmcnt(31)
	v_lshlrev_b32_e32 v146, 16, v182
	v_and_b32_e32 v147, 0xffff0000, v182
	v_lshlrev_b32_e32 v182, 16, v183
	v_and_b32_e32 v183, 0xffff0000, v183
	v_pk_mul_f32 v[146:147], v[146:147], s[74:75] op_sel_hi:[1,0]
	v_pk_mul_f32 v[182:183], v[182:183], s[74:75] op_sel_hi:[1,0]
	v_pk_fma_f32 v[84:85], v[84:85], 0.5, v[146:147] op_sel_hi:[1,0,1]
	v_pk_fma_f32 v[86:87], v[86:87], 0.5, v[182:183] op_sel_hi:[1,0,1]
	global_store_dwordx4 v139, v[84:87], s[16:17] offset:512
	s_waitcnt vmcnt(31)
	v_lshlrev_b32_e32 v146, 16, v184
	v_and_b32_e32 v147, 0xffff0000, v184
	v_lshlrev_b32_e32 v184, 16, v185
	v_and_b32_e32 v185, 0xffff0000, v185
	v_pk_mul_f32 v[146:147], v[146:147], s[74:75] op_sel_hi:[1,0]
	v_pk_mul_f32 v[184:185], v[184:185], s[74:75] op_sel_hi:[1,0]
	v_pk_fma_f32 v[80:81], v[80:81], 0.5, v[146:147] op_sel_hi:[1,0,1]
	v_pk_fma_f32 v[82:83], v[82:83], 0.5, v[184:185] op_sel_hi:[1,0,1]
	global_store_dwordx4 v139, v[80:83], s[16:17] offset:576
	s_waitcnt vmcnt(31)
	v_lshlrev_b32_e32 v146, 16, v186
	v_and_b32_e32 v147, 0xffff0000, v186
	v_lshlrev_b32_e32 v186, 16, v187
	v_and_b32_e32 v187, 0xffff0000, v187
	v_pk_mul_f32 v[146:147], v[146:147], s[74:75] op_sel_hi:[1,0]
	v_pk_mul_f32 v[186:187], v[186:187], s[74:75] op_sel_hi:[1,0]
	v_pk_fma_f32 v[76:77], v[76:77], 0.5, v[146:147] op_sel_hi:[1,0,1]
	v_pk_fma_f32 v[78:79], v[78:79], 0.5, v[186:187] op_sel_hi:[1,0,1]
	s_add_u32 s16, s16, 0x20000
	s_addc_u32 s17, s17, 0
	global_store_dwordx4 v139, v[76:79], s[16:17] offset:0
	s_waitcnt vmcnt(31)
	v_lshlrev_b32_e32 v146, 16, v188
	v_and_b32_e32 v147, 0xffff0000, v188
	v_lshlrev_b32_e32 v188, 16, v189
	v_and_b32_e32 v189, 0xffff0000, v189
	v_pk_mul_f32 v[146:147], v[146:147], s[74:75] op_sel_hi:[1,0]
	v_pk_mul_f32 v[188:189], v[188:189], s[74:75] op_sel_hi:[1,0]
	v_pk_fma_f32 v[72:73], v[72:73], 0.5, v[146:147] op_sel_hi:[1,0,1]
	v_pk_fma_f32 v[74:75], v[74:75], 0.5, v[188:189] op_sel_hi:[1,0,1]
	global_store_dwordx4 v139, v[72:75], s[16:17] offset:64
	s_waitcnt vmcnt(31)
	v_lshlrev_b32_e32 v146, 16, v190
	v_and_b32_e32 v147, 0xffff0000, v190
	v_lshlrev_b32_e32 v190, 16, v191
	v_and_b32_e32 v191, 0xffff0000, v191
	v_pk_mul_f32 v[146:147], v[146:147], s[74:75] op_sel_hi:[1,0]
	v_pk_mul_f32 v[190:191], v[190:191], s[74:75] op_sel_hi:[1,0]
	v_pk_fma_f32 v[68:69], v[68:69], 0.5, v[146:147] op_sel_hi:[1,0,1]
	v_pk_fma_f32 v[70:71], v[70:71], 0.5, v[190:191] op_sel_hi:[1,0,1]
	global_store_dwordx4 v139, v[68:71], s[16:17] offset:512
	s_waitcnt vmcnt(31)
	v_lshlrev_b32_e32 v146, 16, v192
	v_and_b32_e32 v147, 0xffff0000, v192
	v_lshlrev_b32_e32 v192, 16, v193
	v_and_b32_e32 v193, 0xffff0000, v193
	v_pk_mul_f32 v[146:147], v[146:147], s[74:75] op_sel_hi:[1,0]
	v_pk_mul_f32 v[192:193], v[192:193], s[74:75] op_sel_hi:[1,0]
	v_pk_fma_f32 v[64:65], v[64:65], 0.5, v[146:147] op_sel_hi:[1,0,1]
	v_pk_fma_f32 v[66:67], v[66:67], 0.5, v[192:193] op_sel_hi:[1,0,1]
	global_store_dwordx4 v139, v[64:67], s[16:17] offset:576
	s_waitcnt vmcnt(31)
	v_lshlrev_b32_e32 v146, 16, v194
	v_and_b32_e32 v147, 0xffff0000, v194
	v_lshlrev_b32_e32 v194, 16, v195
	v_and_b32_e32 v195, 0xffff0000, v195
	v_pk_mul_f32 v[146:147], v[146:147], s[74:75] op_sel_hi:[1,0]
	v_pk_mul_f32 v[194:195], v[194:195], s[74:75] op_sel_hi:[1,0]
	v_pk_fma_f32 v[60:61], v[60:61], 0.5, v[146:147] op_sel_hi:[1,0,1]
	v_pk_fma_f32 v[62:63], v[62:63], 0.5, v[194:195] op_sel_hi:[1,0,1]
	s_add_u32 s16, s16, 0xa0000
	s_addc_u32 s17, s17, 0
	global_store_dwordx4 v139, v[60:63], s[16:17] offset:0
	s_waitcnt vmcnt(31)
	v_lshlrev_b32_e32 v146, 16, v208
	v_and_b32_e32 v147, 0xffff0000, v208
	v_lshlrev_b32_e32 v208, 16, v209
	v_and_b32_e32 v209, 0xffff0000, v209
	v_pk_mul_f32 v[146:147], v[146:147], s[74:75] op_sel_hi:[1,0]
	v_pk_mul_f32 v[208:209], v[208:209], s[74:75] op_sel_hi:[1,0]
	v_pk_fma_f32 v[56:57], v[56:57], 0.5, v[146:147] op_sel_hi:[1,0,1]
	v_pk_fma_f32 v[58:59], v[58:59], 0.5, v[208:209] op_sel_hi:[1,0,1]
	global_store_dwordx4 v139, v[56:59], s[16:17] offset:64
	s_waitcnt vmcnt(31)
	v_lshlrev_b32_e32 v146, 16, v210
	v_and_b32_e32 v147, 0xffff0000, v210
	v_lshlrev_b32_e32 v210, 16, v211
	v_and_b32_e32 v211, 0xffff0000, v211
	v_pk_mul_f32 v[146:147], v[146:147], s[74:75] op_sel_hi:[1,0]
	v_pk_mul_f32 v[210:211], v[210:211], s[74:75] op_sel_hi:[1,0]
	v_pk_fma_f32 v[52:53], v[52:53], 0.5, v[146:147] op_sel_hi:[1,0,1]
	v_pk_fma_f32 v[54:55], v[54:55], 0.5, v[210:211] op_sel_hi:[1,0,1]
	global_store_dwordx4 v139, v[52:55], s[16:17] offset:512
	s_waitcnt vmcnt(31)
	v_lshlrev_b32_e32 v146, 16, v212
	v_and_b32_e32 v147, 0xffff0000, v212
	v_lshlrev_b32_e32 v212, 16, v213
	v_and_b32_e32 v213, 0xffff0000, v213
	v_pk_mul_f32 v[146:147], v[146:147], s[74:75] op_sel_hi:[1,0]
	v_pk_mul_f32 v[212:213], v[212:213], s[74:75] op_sel_hi:[1,0]
	v_pk_fma_f32 v[48:49], v[48:49], 0.5, v[146:147] op_sel_hi:[1,0,1]
	v_pk_fma_f32 v[50:51], v[50:51], 0.5, v[212:213] op_sel_hi:[1,0,1]
	global_store_dwordx4 v139, v[48:51], s[16:17] offset:576
	s_waitcnt vmcnt(31)
	v_lshlrev_b32_e32 v146, 16, v214
	v_and_b32_e32 v147, 0xffff0000, v214
	v_lshlrev_b32_e32 v214, 16, v215
	v_and_b32_e32 v215, 0xffff0000, v215
	v_pk_mul_f32 v[146:147], v[146:147], s[74:75] op_sel_hi:[1,0]
	v_pk_mul_f32 v[214:215], v[214:215], s[74:75] op_sel_hi:[1,0]
	v_pk_fma_f32 v[44:45], v[44:45], 0.5, v[146:147] op_sel_hi:[1,0,1]
	v_pk_fma_f32 v[46:47], v[46:47], 0.5, v[214:215] op_sel_hi:[1,0,1]
	s_add_u32 s16, s16, 0x20000
	s_addc_u32 s17, s17, 0
	global_store_dwordx4 v139, v[44:47], s[16:17] offset:0
	s_waitcnt vmcnt(31)
	v_lshlrev_b32_e32 v146, 16, v216
	v_and_b32_e32 v147, 0xffff0000, v216
	v_lshlrev_b32_e32 v216, 16, v217
	v_and_b32_e32 v217, 0xffff0000, v217
	v_pk_mul_f32 v[146:147], v[146:147], s[74:75] op_sel_hi:[1,0]
	v_pk_mul_f32 v[216:217], v[216:217], s[74:75] op_sel_hi:[1,0]
	v_pk_fma_f32 v[40:41], v[40:41], 0.5, v[146:147] op_sel_hi:[1,0,1]
	v_pk_fma_f32 v[42:43], v[42:43], 0.5, v[216:217] op_sel_hi:[1,0,1]
	global_store_dwordx4 v139, v[40:43], s[16:17] offset:64
	s_waitcnt vmcnt(31)
	v_lshlrev_b32_e32 v146, 16, v218
	v_and_b32_e32 v147, 0xffff0000, v218
	v_lshlrev_b32_e32 v218, 16, v219
	v_and_b32_e32 v219, 0xffff0000, v219
	v_pk_mul_f32 v[146:147], v[146:147], s[74:75] op_sel_hi:[1,0]
	v_pk_mul_f32 v[218:219], v[218:219], s[74:75] op_sel_hi:[1,0]
	v_pk_fma_f32 v[36:37], v[36:37], 0.5, v[146:147] op_sel_hi:[1,0,1]
	v_pk_fma_f32 v[38:39], v[38:39], 0.5, v[218:219] op_sel_hi:[1,0,1]
	global_store_dwordx4 v139, v[36:39], s[16:17] offset:512
	s_waitcnt vmcnt(31)
	v_lshlrev_b32_e32 v146, 16, v220
	v_and_b32_e32 v147, 0xffff0000, v220
	v_lshlrev_b32_e32 v220, 16, v221
	v_and_b32_e32 v221, 0xffff0000, v221
	v_pk_mul_f32 v[146:147], v[146:147], s[74:75] op_sel_hi:[1,0]
	v_pk_mul_f32 v[220:221], v[220:221], s[74:75] op_sel_hi:[1,0]
	v_pk_fma_f32 v[32:33], v[32:33], 0.5, v[146:147] op_sel_hi:[1,0,1]
	v_pk_fma_f32 v[34:35], v[34:35], 0.5, v[220:221] op_sel_hi:[1,0,1]
	global_store_dwordx4 v139, v[32:35], s[16:17] offset:576
	s_waitcnt vmcnt(31)
	v_lshlrev_b32_e32 v146, 16, v222
	v_and_b32_e32 v147, 0xffff0000, v222
	v_lshlrev_b32_e32 v222, 16, v223
	v_and_b32_e32 v223, 0xffff0000, v223
	v_pk_mul_f32 v[146:147], v[146:147], s[74:75] op_sel_hi:[1,0]
	v_pk_mul_f32 v[222:223], v[222:223], s[74:75] op_sel_hi:[1,0]
	v_pk_fma_f32 v[28:29], v[28:29], 0.5, v[146:147] op_sel_hi:[1,0,1]
	v_pk_fma_f32 v[30:31], v[30:31], 0.5, v[222:223] op_sel_hi:[1,0,1]
	s_add_u32 s16, s16, 0x20000
	s_addc_u32 s17, s17, 0
	global_store_dwordx4 v139, v[28:31], s[16:17] offset:0
	s_waitcnt vmcnt(31)
	v_lshlrev_b32_e32 v146, 16, v224
	v_and_b32_e32 v147, 0xffff0000, v224
	v_lshlrev_b32_e32 v224, 16, v225
	v_and_b32_e32 v225, 0xffff0000, v225
	v_pk_mul_f32 v[146:147], v[146:147], s[74:75] op_sel_hi:[1,0]
	v_pk_mul_f32 v[224:225], v[224:225], s[74:75] op_sel_hi:[1,0]
	v_pk_fma_f32 v[24:25], v[24:25], 0.5, v[146:147] op_sel_hi:[1,0,1]
	v_pk_fma_f32 v[26:27], v[26:27], 0.5, v[224:225] op_sel_hi:[1,0,1]
	global_store_dwordx4 v139, v[24:27], s[16:17] offset:64
	s_waitcnt vmcnt(31)
	v_lshlrev_b32_e32 v146, 16, v226
	v_and_b32_e32 v147, 0xffff0000, v226
	v_lshlrev_b32_e32 v226, 16, v227
	v_and_b32_e32 v227, 0xffff0000, v227
	v_pk_mul_f32 v[146:147], v[146:147], s[74:75] op_sel_hi:[1,0]
	v_pk_mul_f32 v[226:227], v[226:227], s[74:75] op_sel_hi:[1,0]
	v_pk_fma_f32 v[20:21], v[20:21], 0.5, v[146:147] op_sel_hi:[1,0,1]
	v_pk_fma_f32 v[22:23], v[22:23], 0.5, v[226:227] op_sel_hi:[1,0,1]
	global_store_dwordx4 v139, v[20:23], s[16:17] offset:512
	s_waitcnt vmcnt(31)
	v_lshlrev_b32_e32 v146, 16, v228
	v_and_b32_e32 v147, 0xffff0000, v228
	v_lshlrev_b32_e32 v228, 16, v229
	v_and_b32_e32 v229, 0xffff0000, v229
	v_pk_mul_f32 v[146:147], v[146:147], s[74:75] op_sel_hi:[1,0]
	v_pk_mul_f32 v[228:229], v[228:229], s[74:75] op_sel_hi:[1,0]
	v_pk_fma_f32 v[16:17], v[16:17], 0.5, v[146:147] op_sel_hi:[1,0,1]
	v_pk_fma_f32 v[18:19], v[18:19], 0.5, v[228:229] op_sel_hi:[1,0,1]
	global_store_dwordx4 v139, v[16:19], s[16:17] offset:576
	s_waitcnt vmcnt(31)
	v_lshlrev_b32_e32 v146, 16, v230
	v_and_b32_e32 v147, 0xffff0000, v230
	v_lshlrev_b32_e32 v230, 16, v231
	v_and_b32_e32 v231, 0xffff0000, v231
	v_pk_mul_f32 v[146:147], v[146:147], s[74:75] op_sel_hi:[1,0]
	v_pk_mul_f32 v[230:231], v[230:231], s[74:75] op_sel_hi:[1,0]
	v_pk_fma_f32 v[12:13], v[12:13], 0.5, v[146:147] op_sel_hi:[1,0,1]
	v_pk_fma_f32 v[14:15], v[14:15], 0.5, v[230:231] op_sel_hi:[1,0,1]
	s_add_u32 s16, s16, 0x20000
	s_addc_u32 s17, s17, 0
	global_store_dwordx4 v139, v[12:15], s[16:17] offset:0
	s_waitcnt vmcnt(30)
	v_lshlrev_b32_e32 v146, 16, v148
	v_and_b32_e32 v147, 0xffff0000, v148
	v_lshlrev_b32_e32 v148, 16, v149
	v_and_b32_e32 v149, 0xffff0000, v149
	v_pk_mul_f32 v[146:147], v[146:147], s[74:75] op_sel_hi:[1,0]
	v_pk_mul_f32 v[148:149], v[148:149], s[74:75] op_sel_hi:[1,0]
	v_pk_fma_f32 v[8:9], v[8:9], 0.5, v[146:147] op_sel_hi:[1,0,1]
	v_pk_fma_f32 v[10:11], v[10:11], 0.5, v[148:149] op_sel_hi:[1,0,1]
	global_store_dwordx4 v139, v[8:11], s[16:17] offset:64
	s_waitcnt vmcnt(29)
	v_lshlrev_b32_e32 v146, 16, v150
	v_and_b32_e32 v147, 0xffff0000, v150
	v_lshlrev_b32_e32 v150, 16, v151
	v_and_b32_e32 v151, 0xffff0000, v151
	v_pk_mul_f32 v[146:147], v[146:147], s[74:75] op_sel_hi:[1,0]
	v_pk_mul_f32 v[150:151], v[150:151], s[74:75] op_sel_hi:[1,0]
	v_pk_fma_f32 v[4:5], v[4:5], 0.5, v[146:147] op_sel_hi:[1,0,1]
	v_pk_fma_f32 v[6:7], v[6:7], 0.5, v[150:151] op_sel_hi:[1,0,1]
	global_store_dwordx4 v139, v[4:7], s[16:17] offset:512
	s_waitcnt vmcnt(28)
	v_lshlrev_b32_e32 v146, 16, v152
	v_and_b32_e32 v147, 0xffff0000, v152
	v_lshlrev_b32_e32 v152, 16, v153
	v_and_b32_e32 v153, 0xffff0000, v153
	v_pk_mul_f32 v[146:147], v[146:147], s[74:75] op_sel_hi:[1,0]
	v_pk_mul_f32 v[152:153], v[152:153], s[74:75] op_sel_hi:[1,0]
	v_pk_fma_f32 v[0:1], v[0:1], 0.5, v[146:147] op_sel_hi:[1,0,1]
	v_pk_fma_f32 v[2:3], v[2:3], 0.5, v[152:153] op_sel_hi:[1,0,1]
	global_store_dwordx4 v139, v[0:3], s[16:17] offset:576
	s_mov_b64 s[16:17], s[12:13]
	s_mov_b64 s[14:15], s[10:11]
	s_and_b64 vcc, exec, s[8:9]
	s_cbranch_vccz .LBB0_118
	s_waitcnt vmcnt(0)
	s_cmpk_gt_u32 s1, 0xff
	s_cbranch_scc1 .LBB0_133
	s_barrier

.LBB0_471:
	v_bfe_u32 v17, v9, 4, 2
	v_and_b32_e32 v18, 15, v9
	v_lshlrev_b32_e32 v19, 4, v17
	v_lshlrev_b32_e32 v9, 2, v9
	s_waitcnt vmcnt(0)
	v_lshl_or_b32 v150, s8, 6, v18
	v_lshl_or_b32 v18, v18, 6, v19
	s_lshl_b32 s8, s8, 13
	v_and_b32_e32 v9, 32, v9
	v_bitop3_b32 v19, v18, s8, v9 bitop3:0xde
	s_lshl_b32 s8, s9, 5
	s_and_b32 s10, s8, 0x60
	s_add_i32 m0, s29, 0x18000
	v_lshl_add_u64 v[6:7], v[6:7], 0, s[6:7]
	s_lshl_b32 s8, s10, 7
	s_waitcnt vmcnt(0)
	s_barrier
	global_load_lds_dwordx4 v[6:7], off
	v_lshl_add_u64 v[4:5], v[4:5], 0, s[6:7]
	s_add_i32 m0, s29, 0x1a000
	s_add_i32 s35, s29, 0x8000
	s_add_i32 s36, s29, 0xa000
	v_bitop3_b32 v151, v18, s8, v9 bitop3:0xde
	global_load_lds_dwordx4 v[4:5], off
	v_lshl_add_u64 v[2:3], v[2:3], 0, s[6:7]
	s_mov_b32 m0, s35
	s_add_u32 s8, s22, 0x160080
	global_load_lds_dwordx4 v[2:3], off
	v_lshl_add_u64 v[0:1], v[0:1], 0, s[6:7]
	s_mov_b32 m0, s36
	s_addc_u32 s9, s23, 0
	global_load_lds_dwordx4 v[0:1], off
	s_add_i32 m0, s29, 0x1c000
	v_lshl_add_u64 v[0:1], s[8:9], 0, v[128:129]
	global_load_lds_dwordx4 v[0:1], off
	v_lshl_add_u64 v[0:1], s[8:9], 0, v[134:135]
	s_add_i32 m0, s29, 0x1e000
	s_movk_i32 s11, 0x1600
	global_load_lds_dwordx4 v[0:1], off
	v_lshl_or_b32 v152, v17, 2, s10
	v_lshrrev_b32_e32 v1, 1, v8
	v_mul_lo_u32 v0, v11, s11
	s_mov_b32 s10, 0x16000
	v_mad_u64_u32 v[0:1], s[8:9], v1, s10, v[0:1]
	v_or_b32_e32 v0, v0, v10
	v_add_lshl_u32 v0, v0, v12, 1
	v_mov_b32_e32 v1, v129
	s_mov_b64 s[12:13], 0x160080
	v_lshl_add_u64 v[136:137], v[0:1], 0, s[12:13]
	v_lshrrev_b32_e32 v1, 1, v13
	v_mul_lo_u32 v0, v15, s11
	v_mad_u64_u32 v[0:1], s[8:9], v1, s10, v[0:1]
	s_waitcnt vmcnt(6)
	s_ashr_i32 s37, s0, 31
	v_or_b32_e32 v0, v0, v14
	s_waitcnt lgkmcnt(0)
	s_cmp_lg_u64 s[14:15], 0
	v_add_lshl_u32 v0, v0, v16, 1
	v_mov_b32_e32 v1, v129
	s_cselect_b64 s[16:17], -1, 0
	v_lshl_add_u64 v[138:139], v[0:1], 0, s[12:13]
	s_mov_b32 s38, 0
	v_add_u32_e32 v153, 0, v19
	s_barrier
	s_branch .LBB0_473

.LBB0_484:
	s_add_u32 s10, s20, 0x100
	s_addc_u32 s11, s21, 0
	s_add_i32 s46, 0, 0x10000
	v_add_u32_e32 v148, s46, v151
	ds_read_b128 v[130:133], v148
	ds_read_b128 v[140:143], v148 offset:1024
	ds_read_b128 v[144:147], v148 offset:2048
	ds_read_b128 v[154:157], v148 offset:3072
	s_cmpk_eq_i32 s45, 0x54
	s_cselect_b32 s25, s19, s11
	s_cselect_b32 s24, s18, s10
	s_cselect_b32 s23, s13, s44
	s_cselect_b32 s22, s12, s43
	v_lshl_add_u64 v[148:149], s[20:21], 0, v[136:137]
	s_add_i32 m0, s29, 0xc000
	ds_read_b128 v[158:161], v153
	ds_read_b128 v[176:179], v153 offset:1024
	ds_read_b128 v[180:183], v153 offset:2048
	ds_read_b128 v[184:187], v153 offset:3072
	ds_read_b128 v[188:191], v153 offset:4096
	ds_read_b128 v[192:195], v153 offset:5120
	ds_read_b128 v[208:211], v153 offset:6144
	ds_read_b128 v[212:215], v153 offset:7168
	global_load_lds_dwordx4 v[148:149], off
	v_lshl_add_u64 v[148:149], s[20:21], 0, v[138:139]
	s_add_i32 m0, s29, 0xe000
	s_nop 0
	global_load_lds_dwordx4 v[148:149], off
	s_waitcnt lgkmcnt(8)
	s_add_i32 s47, 0, 0x14000
	v_add_u32_e32 v228, s47, v151
	ds_read_b128 v[216:219], v228
	ds_read_b128 v[220:223], v228 offset:1024
	ds_read_b128 v[224:227], v228 offset:2048
	ds_read_b128 v[228:231], v228 offset:3072
	s_barrier
	s_waitcnt lgkmcnt(0)
	s_setprio 1
	s_waitcnt lgkmcnt(0)
	v_mfma_f32_16x16x32_bf16 v[124:127], v[130:133], v[158:161], v[124:127]
	v_mfma_f32_16x16x32_bf16 v[120:123], v[144:147], v[158:161], v[120:123]
	v_mfma_f32_16x16x32_bf16 v[108:111], v[130:133], v[180:183], v[108:111]
	v_mfma_f32_16x16x32_bf16 v[104:107], v[144:147], v[180:183], v[104:107]
	v_mfma_f32_16x16x32_bf16 v[92:95], v[130:133], v[188:191], v[92:95]
	v_mfma_f32_16x16x32_bf16 v[88:91], v[144:147], v[188:191], v[88:91]
	v_mfma_f32_16x16x32_bf16 v[76:79], v[130:133], v[208:211], v[76:79]
	v_mfma_f32_16x16x32_bf16 v[72:75], v[144:147], v[208:211], v[72:75]
	v_mfma_f32_16x16x32_bf16 v[124:127], v[140:143], v[176:179], v[124:127]
	v_mfma_f32_16x16x32_bf16 v[120:123], v[154:157], v[176:179], v[120:123]
	v_mfma_f32_16x16x32_bf16 v[108:111], v[140:143], v[184:187], v[108:111]
	v_mfma_f32_16x16x32_bf16 v[104:107], v[154:157], v[184:187], v[104:107]
	v_mfma_f32_16x16x32_bf16 v[92:95], v[140:143], v[192:195], v[92:95]
	v_mfma_f32_16x16x32_bf16 v[88:91], v[154:157], v[192:195], v[88:91]
	v_mfma_f32_16x16x32_bf16 v[76:79], v[140:143], v[212:215], v[76:79]
	v_mfma_f32_16x16x32_bf16 v[72:75], v[154:157], v[212:215], v[72:75]
	s_setprio 0
	s_waitcnt lgkmcnt(0)
	s_setprio 1
	s_waitcnt lgkmcnt(0)
	v_mfma_f32_16x16x32_bf16 v[116:119], v[216:219], v[158:161], v[116:119]
	v_mfma_f32_16x16x32_bf16 v[112:115], v[224:227], v[158:161], v[112:115]
	v_mfma_f32_16x16x32_bf16 v[100:103], v[216:219], v[180:183], v[100:103]
	v_mfma_f32_16x16x32_bf16 v[96:99], v[224:227], v[180:183], v[96:99]
	v_mfma_f32_16x16x32_bf16 v[84:87], v[216:219], v[188:191], v[84:87]
	v_mfma_f32_16x16x32_bf16 v[80:83], v[224:227], v[188:191], v[80:83]
	v_mfma_f32_16x16x32_bf16 v[68:71], v[216:219], v[208:211], v[68:71]
	v_mfma_f32_16x16x32_bf16 v[64:67], v[224:227], v[208:211], v[64:67]
	v_mfma_f32_16x16x32_bf16 v[116:119], v[220:223], v[176:179], v[116:119]
	v_mfma_f32_16x16x32_bf16 v[112:115], v[228:231], v[176:179], v[112:115]
	v_mfma_f32_16x16x32_bf16 v[100:103], v[220:223], v[184:187], v[100:103]
	v_mfma_f32_16x16x32_bf16 v[96:99], v[228:231], v[184:187], v[96:99]
	v_mfma_f32_16x16x32_bf16 v[84:87], v[220:223], v[192:195], v[84:87]
	v_mfma_f32_16x16x32_bf16 v[80:83], v[228:231], v[192:195], v[80:83]
	v_mfma_f32_16x16x32_bf16 v[68:71], v[220:223], v[212:215], v[68:71]
	v_mfma_f32_16x16x32_bf16 v[64:67], v[228:231], v[212:215], v[64:67]
	s_setprio 0
	s_barrier
	s_add_i32 s20, s46, s28
	v_lshl_add_u64 v[148:149], s[22:23], 0, v[128:129]
	s_mov_b32 m0, s20
	v_lshl_add_u64 v[232:233], s[22:23], 0, v[134:135]
	global_load_lds_dwordx4 v[148:149], off
	s_add_i32 m0, s20, 0x2000
	s_nop 0
	global_load_lds_dwordx4 v[232:233], off
	s_mov_b32 m0, s29
	v_lshl_add_u64 v[234:235], s[24:25], 0, v[128:129]
	ds_read_b128 v[158:161], v153 offset:16384
	ds_read_b128 v[176:179], v153 offset:17408
	ds_read_b128 v[180:183], v153 offset:18432
	ds_read_b128 v[184:187], v153 offset:19456
	ds_read_b128 v[188:191], v153 offset:20480
	ds_read_b128 v[192:195], v153 offset:21504
	ds_read_b128 v[208:211], v153 offset:22528
	ds_read_b128 v[212:215], v153 offset:23552
	global_load_lds_dwordx4 v[234:235], off
	v_lshl_add_u64 v[236:237], s[24:25], 0, v[134:135]
	s_mov_b32 m0, s30
	s_nop 0
	global_load_lds_dwordx4 v[236:237], off
	s_waitcnt vmcnt(4)
	s_barrier
	s_waitcnt lgkmcnt(0)
	s_setprio 1
	s_waitcnt lgkmcnt(0)
	v_mfma_f32_16x16x32_bf16 v[60:63], v[130:133], v[158:161], v[60:63]
	v_mfma_f32_16x16x32_bf16 v[56:59], v[144:147], v[158:161], v[56:59]
	v_mfma_f32_16x16x32_bf16 v[44:47], v[130:133], v[180:183], v[44:47]
	v_mfma_f32_16x16x32_bf16 v[40:43], v[144:147], v[180:183], v[40:43]
	v_mfma_f32_16x16x32_bf16 v[28:31], v[130:133], v[188:191], v[28:31]
	v_mfma_f32_16x16x32_bf16 v[24:27], v[144:147], v[188:191], v[24:27]
	v_mfma_f32_16x16x32_bf16 v[12:15], v[130:133], v[208:211], v[12:15]
	v_mfma_f32_16x16x32_bf16 v[8:11], v[144:147], v[208:211], v[8:11]
	v_mfma_f32_16x16x32_bf16 v[60:63], v[140:143], v[176:179], v[60:63]
	v_mfma_f32_16x16x32_bf16 v[56:59], v[154:157], v[176:179], v[56:59]
	v_mfma_f32_16x16x32_bf16 v[44:47], v[140:143], v[184:187], v[44:47]
	v_mfma_f32_16x16x32_bf16 v[40:43], v[154:157], v[184:187], v[40:43]
	v_mfma_f32_16x16x32_bf16 v[28:31], v[140:143], v[192:195], v[28:31]
	v_mfma_f32_16x16x32_bf16 v[24:27], v[154:157], v[192:195], v[24:27]
	v_mfma_f32_16x16x32_bf16 v[12:15], v[140:143], v[212:215], v[12:15]
	v_mfma_f32_16x16x32_bf16 v[8:11], v[154:157], v[212:215], v[8:11]
	s_setprio 0
	s_add_u32 s20, s22, 0x160000
	s_addc_u32 s21, s23, 0
	s_add_i32 s46, s47, s28
	v_lshl_add_u64 v[130:131], s[20:21], 0, v[128:129]
	s_mov_b32 m0, s46
	s_nop 0
	global_load_lds_dwordx4 v[130:131], off
	v_lshl_add_u64 v[130:131], s[20:21], 0, v[134:135]
	s_add_i32 m0, s46, 0x2000
	s_nop 0
	global_load_lds_dwordx4 v[130:131], off
	s_setprio 1
	v_mfma_f32_16x16x32_bf16 v[52:55], v[216:219], v[158:161], v[52:55]
	v_mfma_f32_16x16x32_bf16 v[48:51], v[224:227], v[158:161], v[48:51]
	v_mfma_f32_16x16x32_bf16 v[36:39], v[216:219], v[180:183], v[36:39]
	v_mfma_f32_16x16x32_bf16 v[32:35], v[224:227], v[180:183], v[32:35]
	v_mfma_f32_16x16x32_bf16 v[20:23], v[216:219], v[188:191], v[20:23]
	v_mfma_f32_16x16x32_bf16 v[16:19], v[224:227], v[188:191], v[16:19]
	v_mfma_f32_16x16x32_bf16 v[4:7], v[216:219], v[208:211], v[4:7]
	v_mfma_f32_16x16x32_bf16 v[0:3], v[224:227], v[208:211], v[0:3]
	v_mfma_f32_16x16x32_bf16 v[52:55], v[220:223], v[176:179], v[52:55]
	v_mfma_f32_16x16x32_bf16 v[48:51], v[228:231], v[176:179], v[48:51]
	v_mfma_f32_16x16x32_bf16 v[36:39], v[220:223], v[184:187], v[36:39]
	v_mfma_f32_16x16x32_bf16 v[32:35], v[228:231], v[184:187], v[32:35]
	v_mfma_f32_16x16x32_bf16 v[20:23], v[220:223], v[192:195], v[20:23]
	v_mfma_f32_16x16x32_bf16 v[16:19], v[228:231], v[192:195], v[16:19]
	v_mfma_f32_16x16x32_bf16 v[4:7], v[220:223], v[212:215], v[4:7]
	v_mfma_f32_16x16x32_bf16 v[0:3], v[228:231], v[212:215], v[0:3]
	s_setprio 0
	s_add_i32 s46, 0, 0x18000
	v_add_u32_e32 v154, s46, v151
	s_barrier
	ds_read_b128 v[130:133], v154
	ds_read_b128 v[140:143], v154 offset:1024
	ds_read_b128 v[144:147], v154 offset:2048
	ds_read_b128 v[154:157], v154 offset:3072
	s_add_u32 s20, s24, 0x160000
	s_addc_u32 s21, s25, 0
	s_mov_b32 m0, s31
	v_lshl_add_u64 v[216:217], s[20:21], 0, v[128:129]
	ds_read_b128 v[158:161], v153 offset:32768
	ds_read_b128 v[176:179], v153 offset:33792
	ds_read_b128 v[180:183], v153 offset:34816
	ds_read_b128 v[184:187], v153 offset:35840
	ds_read_b128 v[188:191], v153 offset:36864
	ds_read_b128 v[192:195], v153 offset:37888
	ds_read_b128 v[208:211], v153 offset:38912
	ds_read_b128 v[212:215], v153 offset:39936
	global_load_lds_dwordx4 v[216:217], off
	v_lshl_add_u64 v[216:217], s[20:21], 0, v[134:135]
	s_mov_b32 m0, s34
	s_nop 0
	global_load_lds_dwordx4 v[216:217], off
	s_waitcnt lgkmcnt(8)
	s_add_i32 s24, 0, 0x1c000
	v_add_u32_e32 v228, s24, v151
	ds_read_b128 v[216:219], v228
	ds_read_b128 v[220:223], v228 offset:1024
	ds_read_b128 v[224:227], v228 offset:2048
	ds_read_b128 v[228:231], v228 offset:3072
	s_barrier
	s_waitcnt lgkmcnt(0)
	s_setprio 1
	s_waitcnt lgkmcnt(0)
	v_mfma_f32_16x16x32_bf16 v[124:127], v[130:133], v[158:161], v[124:127]
	v_mfma_f32_16x16x32_bf16 v[120:123], v[144:147], v[158:161], v[120:123]
	v_mfma_f32_16x16x32_bf16 v[108:111], v[130:133], v[180:183], v[108:111]
	v_mfma_f32_16x16x32_bf16 v[104:107], v[144:147], v[180:183], v[104:107]
	v_mfma_f32_16x16x32_bf16 v[92:95], v[130:133], v[188:191], v[92:95]
	v_mfma_f32_16x16x32_bf16 v[88:91], v[144:147], v[188:191], v[88:91]
	v_mfma_f32_16x16x32_bf16 v[76:79], v[130:133], v[208:211], v[76:79]
	v_mfma_f32_16x16x32_bf16 v[72:75], v[144:147], v[208:211], v[72:75]
	v_mfma_f32_16x16x32_bf16 v[124:127], v[140:143], v[176:179], v[124:127]
	v_mfma_f32_16x16x32_bf16 v[120:123], v[154:157], v[176:179], v[120:123]
	v_mfma_f32_16x16x32_bf16 v[108:111], v[140:143], v[184:187], v[108:111]
	v_mfma_f32_16x16x32_bf16 v[104:107], v[154:157], v[184:187], v[104:107]
	v_mfma_f32_16x16x32_bf16 v[92:95], v[140:143], v[192:195], v[92:95]
	v_mfma_f32_16x16x32_bf16 v[88:91], v[154:157], v[192:195], v[88:91]
	v_mfma_f32_16x16x32_bf16 v[76:79], v[140:143], v[212:215], v[76:79]
	v_mfma_f32_16x16x32_bf16 v[72:75], v[154:157], v[212:215], v[72:75]
	s_setprio 0
	s_waitcnt lgkmcnt(0)
	s_setprio 1
	s_waitcnt lgkmcnt(0)
	v_mfma_f32_16x16x32_bf16 v[116:119], v[216:219], v[158:161], v[116:119]
	v_mfma_f32_16x16x32_bf16 v[112:115], v[224:227], v[158:161], v[112:115]
	v_mfma_f32_16x16x32_bf16 v[100:103], v[216:219], v[180:183], v[100:103]
	v_mfma_f32_16x16x32_bf16 v[96:99], v[224:227], v[180:183], v[96:99]
	v_mfma_f32_16x16x32_bf16 v[84:87], v[216:219], v[188:191], v[84:87]
	v_mfma_f32_16x16x32_bf16 v[80:83], v[224:227], v[188:191], v[80:83]
	v_mfma_f32_16x16x32_bf16 v[68:71], v[216:219], v[208:211], v[68:71]
	v_mfma_f32_16x16x32_bf16 v[64:67], v[224:227], v[208:211], v[64:67]
	v_mfma_f32_16x16x32_bf16 v[116:119], v[220:223], v[176:179], v[116:119]
	v_mfma_f32_16x16x32_bf16 v[112:115], v[228:231], v[176:179], v[112:115]
	v_mfma_f32_16x16x32_bf16 v[100:103], v[220:223], v[184:187], v[100:103]
	v_mfma_f32_16x16x32_bf16 v[96:99], v[228:231], v[184:187], v[96:99]
	v_mfma_f32_16x16x32_bf16 v[84:87], v[220:223], v[192:195], v[84:87]
	v_mfma_f32_16x16x32_bf16 v[80:83], v[228:231], v[192:195], v[80:83]
	v_mfma_f32_16x16x32_bf16 v[68:71], v[220:223], v[212:215], v[68:71]
	v_mfma_f32_16x16x32_bf16 v[64:67], v[228:231], v[212:215], v[64:67]
	s_setprio 0
	s_barrier
	s_add_i32 s20, s46, s28
	v_lshl_add_u64 v[148:149], v[148:149], 0, s[6:7]
	s_mov_b32 m0, s20
	global_load_lds_dwordx4 v[148:149], off
	v_lshl_add_u64 v[148:149], v[232:233], 0, s[6:7]
	s_add_i32 m0, s20, 0x2000
	s_nop 0
	global_load_lds_dwordx4 v[148:149], off
	s_mov_b32 m0, s35
	v_lshl_add_u64 v[148:149], v[234:235], 0, s[6:7]
	ds_read_b128 v[158:161], v153 offset:49152
	ds_read_b128 v[176:179], v153 offset:50176
	ds_read_b128 v[180:183], v153 offset:51200
	ds_read_b128 v[184:187], v153 offset:52224
	ds_read_b128 v[188:191], v153 offset:53248
	ds_read_b128 v[192:195], v153 offset:54272
	ds_read_b128 v[208:211], v153 offset:55296
	ds_read_b128 v[212:215], v153 offset:56320
	global_load_lds_dwordx4 v[148:149], off
	v_lshl_add_u64 v[148:149], v[236:237], 0, s[6:7]
	s_mov_b32 m0, s36
	s_nop 0
	global_load_lds_dwordx4 v[148:149], off
	s_waitcnt vmcnt(4)
	s_barrier
	s_waitcnt lgkmcnt(0)
	s_setprio 1
	s_waitcnt lgkmcnt(0)
	v_mfma_f32_16x16x32_bf16 v[60:63], v[130:133], v[158:161], v[60:63]
	v_mfma_f32_16x16x32_bf16 v[56:59], v[144:147], v[158:161], v[56:59]
	v_mfma_f32_16x16x32_bf16 v[44:47], v[130:133], v[180:183], v[44:47]
	v_mfma_f32_16x16x32_bf16 v[40:43], v[144:147], v[180:183], v[40:43]
	v_mfma_f32_16x16x32_bf16 v[28:31], v[130:133], v[188:191], v[28:31]
	v_mfma_f32_16x16x32_bf16 v[24:27], v[144:147], v[188:191], v[24:27]
	v_mfma_f32_16x16x32_bf16 v[12:15], v[130:133], v[208:211], v[12:15]
	v_mfma_f32_16x16x32_bf16 v[8:11], v[144:147], v[208:211], v[8:11]
	v_mfma_f32_16x16x32_bf16 v[60:63], v[140:143], v[176:179], v[60:63]
	v_mfma_f32_16x16x32_bf16 v[56:59], v[154:157], v[176:179], v[56:59]
	v_mfma_f32_16x16x32_bf16 v[44:47], v[140:143], v[184:187], v[44:47]
	v_mfma_f32_16x16x32_bf16 v[40:43], v[154:157], v[184:187], v[40:43]
	v_mfma_f32_16x16x32_bf16 v[28:31], v[140:143], v[192:195], v[28:31]
	v_mfma_f32_16x16x32_bf16 v[24:27], v[154:157], v[192:195], v[24:27]
	v_mfma_f32_16x16x32_bf16 v[12:15], v[140:143], v[212:215], v[12:15]
	v_mfma_f32_16x16x32_bf16 v[8:11], v[154:157], v[212:215], v[8:11]
	s_setprio 0
	s_add_u32 s20, s22, 0x160080
	s_addc_u32 s21, s23, 0
	s_add_i32 s22, s24, s28
	v_lshl_add_u64 v[130:131], s[20:21], 0, v[128:129]
	s_mov_b32 m0, s22
	s_nop 0
	global_load_lds_dwordx4 v[130:131], off
	v_lshl_add_u64 v[130:131], s[20:21], 0, v[134:135]
	s_add_i32 m0, s22, 0x2000
	s_nop 0
	global_load_lds_dwordx4 v[130:131], off
	s_setprio 1
	v_mfma_f32_16x16x32_bf16 v[52:55], v[216:219], v[158:161], v[52:55]
	v_mfma_f32_16x16x32_bf16 v[48:51], v[224:227], v[158:161], v[48:51]
	v_mfma_f32_16x16x32_bf16 v[36:39], v[216:219], v[180:183], v[36:39]
	v_mfma_f32_16x16x32_bf16 v[32:35], v[224:227], v[180:183], v[32:35]
	v_mfma_f32_16x16x32_bf16 v[20:23], v[216:219], v[188:191], v[20:23]
	v_mfma_f32_16x16x32_bf16 v[16:19], v[224:227], v[188:191], v[16:19]
	v_mfma_f32_16x16x32_bf16 v[4:7], v[216:219], v[208:211], v[4:7]
	v_mfma_f32_16x16x32_bf16 v[0:3], v[224:227], v[208:211], v[0:3]
	v_mfma_f32_16x16x32_bf16 v[52:55], v[220:223], v[176:179], v[52:55]
	v_mfma_f32_16x16x32_bf16 v[48:51], v[228:231], v[176:179], v[48:51]
	v_mfma_f32_16x16x32_bf16 v[36:39], v[220:223], v[184:187], v[36:39]
	v_mfma_f32_16x16x32_bf16 v[32:35], v[228:231], v[184:187], v[32:35]
	v_mfma_f32_16x16x32_bf16 v[20:23], v[220:223], v[192:195], v[20:23]
	v_mfma_f32_16x16x32_bf16 v[16:19], v[228:231], v[192:195], v[16:19]
	v_mfma_f32_16x16x32_bf16 v[4:7], v[220:223], v[212:215], v[4:7]
	v_mfma_f32_16x16x32_bf16 v[0:3], v[228:231], v[212:215], v[0:3]
	s_setprio 0
	s_add_i32 s45, s45, 2
	s_add_u32 s43, s43, 0x100
	s_addc_u32 s44, s44, 0
	s_cmpk_gt_u32 s45, 0x55
	s_mov_b64 s[20:21], s[10:11]
	s_barrier
	s_cbranch_scc0 .LBB0_484
	v_lshl_add_u32 v130, s42, 8, v150
	v_lshl_or_b32 v131, s41, 8, v152
	v_lshl_add_u32 v131, v130, 11, v131
	v_lshlrev_b32_e32 v132, 1, v131
	v_lshlrev_b32_e32 v133, 2, v131
	s_and_b64 vcc, exec, s[16:17]
	s_cbranch_vccz .Le484_bf16
	s_mov_b64 s[20:21], s[14:15]
	s_mov_b64 s[22:23], s[76:77]
	global_load_dwordx4 v[142:145], v133, s[20:21] offset:0
	global_load_dwordx4 v[154:157], v133, s[20:21] offset:64
	global_load_dwordx4 v[158:161], v133, s[20:21] offset:512
	global_load_dwordx4 v[176:179], v133, s[20:21] offset:576
	s_add_u32 s20, s20, 0x20000
	s_addc_u32 s21, s21, 0
	global_load_dwordx4 v[180:183], v133, s[20:21] offset:0
	global_load_dwordx4 v[184:187], v133, s[20:21] offset:64
	global_load_dwordx4 v[188:191], v133, s[20:21] offset:512
	global_load_dwordx4 v[192:195], v133, s[20:21] offset:576
	s_add_u32 s20, s20, 0x20000
	s_addc_u32 s21, s21, 0
	global_load_dwordx4 v[208:211], v133, s[20:21] offset:0
	global_load_dwordx4 v[212:215], v133, s[20:21] offset:64
	global_load_dwordx4 v[216:219], v133, s[20:21] offset:512
	global_load_dwordx4 v[220:223], v133, s[20:21] offset:576
	s_add_u32 s20, s20, 0x20000
	s_addc_u32 s21, s21, 0
	global_load_dwordx4 v[224:227], v133, s[20:21] offset:0
	global_load_dwordx4 v[228:231], v133, s[20:21] offset:64
	s_waitcnt vmcnt(13)
	v_pk_mul_f32 v[142:143], v[142:143], s[74:75] op_sel_hi:[1,0]
	v_pk_mul_f32 v[144:145], v[144:145], s[74:75] op_sel_hi:[1,0]
	v_pk_fma_f32 v[124:125], v[124:125], 0.5, v[142:143] op_sel_hi:[1,0,1]
	v_pk_fma_f32 v[126:127], v[126:127], 0.5, v[144:145] op_sel_hi:[1,0,1]
	global_store_dwordx4 v133, v[124:127], s[22:23] offset:0
	global_load_dwordx4 v[142:145], v133, s[20:21] offset:512
	s_waitcnt vmcnt(14)
	v_pk_mul_f32 v[154:155], v[154:155], s[74:75] op_sel_hi:[1,0]
	v_pk_mul_f32 v[156:157], v[156:157], s[74:75] op_sel_hi:[1,0]
	v_pk_fma_f32 v[120:121], v[120:121], 0.5, v[154:155] op_sel_hi:[1,0,1]
	v_pk_fma_f32 v[122:123], v[122:123], 0.5, v[156:157] op_sel_hi:[1,0,1]
	global_store_dwordx4 v133, v[120:123], s[22:23] offset:64
	global_load_dwordx4 v[154:157], v133, s[20:21] offset:576
	s_waitcnt vmcnt(15)
	v_pk_mul_f32 v[158:159], v[158:159], s[74:75] op_sel_hi:[1,0]
	v_pk_mul_f32 v[160:161], v[160:161], s[74:75] op_sel_hi:[1,0]
	v_pk_fma_f32 v[116:117], v[116:117], 0.5, v[158:159] op_sel_hi:[1,0,1]
	v_pk_fma_f32 v[118:119], v[118:119], 0.5, v[160:161] op_sel_hi:[1,0,1]
	global_store_dwordx4 v133, v[116:119], s[22:23] offset:512
	s_add_u32 s20, s20, 0xa0000
	s_addc_u32 s21, s21, 0
	global_load_dwordx4 v[158:161], v133, s[20:21] offset:0
	s_waitcnt vmcnt(16)
	v_pk_mul_f32 v[176:177], v[176:177], s[74:75] op_sel_hi:[1,0]
	v_pk_mul_f32 v[178:179], v[178:179], s[74:75] op_sel_hi:[1,0]
	v_pk_fma_f32 v[112:113], v[112:113], 0.5, v[176:177] op_sel_hi:[1,0,1]
	v_pk_fma_f32 v[114:115], v[114:115], 0.5, v[178:179] op_sel_hi:[1,0,1]
	global_store_dwordx4 v133, v[112:115], s[22:23] offset:576
	global_load_dwordx4 v[176:179], v133, s[20:21] offset:64
	s_waitcnt vmcnt(17)
	v_pk_mul_f32 v[180:181], v[180:181], s[74:75] op_sel_hi:[1,0]
	v_pk_mul_f32 v[182:183], v[182:183], s[74:75] op_sel_hi:[1,0]
	v_pk_fma_f32 v[108:109], v[108:109], 0.5, v[180:181] op_sel_hi:[1,0,1]
	v_pk_fma_f32 v[110:111], v[110:111], 0.5, v[182:183] op_sel_hi:[1,0,1]
	s_add_u32 s22, s22, 0x20000
	s_addc_u32 s23, s23, 0
	global_store_dwordx4 v133, v[108:111], s[22:23] offset:0
	global_load_dwordx4 v[180:183], v133, s[20:21] offset:512
	s_waitcnt vmcnt(18)
	v_pk_mul_f32 v[184:185], v[184:185], s[74:75] op_sel_hi:[1,0]
	v_pk_mul_f32 v[186:187], v[186:187], s[74:75] op_sel_hi:[1,0]
	v_pk_fma_f32 v[104:105], v[104:105], 0.5, v[184:185] op_sel_hi:[1,0,1]
	v_pk_fma_f32 v[106:107], v[106:107], 0.5, v[186:187] op_sel_hi:[1,0,1]
	global_store_dwordx4 v133, v[104:107], s[22:23] offset:64
	global_load_dwordx4 v[184:187], v133, s[20:21] offset:576
	s_waitcnt vmcnt(19)
	v_pk_mul_f32 v[188:189], v[188:189], s[74:75] op_sel_hi:[1,0]
	v_pk_mul_f32 v[190:191], v[190:191], s[74:75] op_sel_hi:[1,0]
	v_pk_fma_f32 v[100:101], v[100:101], 0.5, v[188:189] op_sel_hi:[1,0,1]
	v_pk_fma_f32 v[102:103], v[102:103], 0.5, v[190:191] op_sel_hi:[1,0,1]
	global_store_dwordx4 v133, v[100:103], s[22:23] offset:512
	s_add_u32 s20, s20, 0x20000
	s_addc_u32 s21, s21, 0
	global_load_dwordx4 v[188:191], v133, s[20:21] offset:0
	s_waitcnt vmcnt(20)
	v_pk_mul_f32 v[192:193], v[192:193], s[74:75] op_sel_hi:[1,0]
	v_pk_mul_f32 v[194:195], v[194:195], s[74:75] op_sel_hi:[1,0]
	v_pk_fma_f32 v[96:97], v[96:97], 0.5, v[192:193] op_sel_hi:[1,0,1]
	v_pk_fma_f32 v[98:99], v[98:99], 0.5, v[194:195] op_sel_hi:[1,0,1]
	global_store_dwordx4 v133, v[96:99], s[22:23] offset:576
	global_load_dwordx4 v[192:195], v133, s[20:21] offset:64
	s_waitcnt vmcnt(21)
	v_pk_mul_f32 v[208:209], v[208:209], s[74:75] op_sel_hi:[1,0]
	v_pk_mul_f32 v[210:211], v[210:211], s[74:75] op_sel_hi:[1,0]
	v_pk_fma_f32 v[92:93], v[92:93], 0.5, v[208:209] op_sel_hi:[1,0,1]
	v_pk_fma_f32 v[94:95], v[94:95], 0.5, v[210:211] op_sel_hi:[1,0,1]
	s_add_u32 s22, s22, 0x20000
	s_addc_u32 s23, s23, 0
	global_store_dwordx4 v133, v[92:95], s[22:23] offset:0
	global_load_dwordx4 v[208:211], v133, s[20:21] offset:512
	s_waitcnt vmcnt(22)
	v_pk_mul_f32 v[212:213], v[212:213], s[74:75] op_sel_hi:[1,0]
	v_pk_mul_f32 v[214:215], v[214:215], s[74:75] op_sel_hi:[1,0]
	v_pk_fma_f32 v[88:89], v[88:89], 0.5, v[212:213] op_sel_hi:[1,0,1]
	v_pk_fma_f32 v[90:91], v[90:91], 0.5, v[214:215] op_sel_hi:[1,0,1]
	global_store_dwordx4 v133, v[88:91], s[22:23] offset:64
	global_load_dwordx4 v[212:215], v133, s[20:21] offset:576
	s_waitcnt vmcnt(23)
	v_pk_mul_f32 v[216:217], v[216:217], s[74:75] op_sel_hi:[1,0]
	v_pk_mul_f32 v[218:219], v[218:219], s[74:75] op_sel_hi:[1,0]
	v_pk_fma_f32 v[84:85], v[84:85], 0.5, v[216:217] op_sel_hi:[1,0,1]
	v_pk_fma_f32 v[86:87], v[86:87], 0.5, v[218:219] op_sel_hi:[1,0,1]
	global_store_dwordx4 v133, v[84:87], s[22:23] offset:512
	s_add_u32 s20, s20, 0x20000
	s_addc_u32 s21, s21, 0
	global_load_dwordx4 v[216:219], v133, s[20:21] offset:0
	s_waitcnt vmcnt(24)
	v_pk_mul_f32 v[220:221], v[220:221], s[74:75] op_sel_hi:[1,0]
	v_pk_mul_f32 v[222:223], v[222:223], s[74:75] op_sel_hi:[1,0]
	v_pk_fma_f32 v[80:81], v[80:81], 0.5, v[220:221] op_sel_hi:[1,0,1]
	v_pk_fma_f32 v[82:83], v[82:83], 0.5, v[222:223] op_sel_hi:[1,0,1]
	global_store_dwordx4 v133, v[80:83], s[22:23] offset:576
	global_load_dwordx4 v[220:223], v133, s[20:21] offset:64
	s_waitcnt vmcnt(25)
	v_pk_mul_f32 v[224:225], v[224:225], s[74:75] op_sel_hi:[1,0]
	v_pk_mul_f32 v[226:227], v[226:227], s[74:75] op_sel_hi:[1,0]
	v_pk_fma_f32 v[76:77], v[76:77], 0.5, v[224:225] op_sel_hi:[1,0,1]
	v_pk_fma_f32 v[78:79], v[78:79], 0.5, v[226:227] op_sel_hi:[1,0,1]
	s_add_u32 s22, s22, 0x20000
	s_addc_u32 s23, s23, 0
	global_store_dwordx4 v133, v[76:79], s[22:23] offset:0
	global_load_dwordx4 v[224:227], v133, s[20:21] offset:512
	s_waitcnt vmcnt(26)
	v_pk_mul_f32 v[228:229], v[228:229], s[74:75] op_sel_hi:[1,0]
	v_pk_mul_f32 v[230:231], v[230:231], s[74:75] op_sel_hi:[1,0]
	v_pk_fma_f32 v[72:73], v[72:73], 0.5, v[228:229] op_sel_hi:[1,0,1]
	v_pk_fma_f32 v[74:75], v[74:75], 0.5, v[230:231] op_sel_hi:[1,0,1]
	global_store_dwordx4 v133, v[72:75], s[22:23] offset:64
	global_load_dwordx4 v[228:231], v133, s[20:21] offset:576
	s_waitcnt vmcnt(26)
	v_pk_mul_f32 v[142:143], v[142:143], s[74:75] op_sel_hi:[1,0]
	v_pk_mul_f32 v[144:145], v[144:145], s[74:75] op_sel_hi:[1,0]
	v_pk_fma_f32 v[68:69], v[68:69], 0.5, v[142:143] op_sel_hi:[1,0,1]
	v_pk_fma_f32 v[70:71], v[70:71], 0.5, v[144:145] op_sel_hi:[1,0,1]
	global_store_dwordx4 v133, v[68:71], s[22:23] offset:512
	s_add_u32 s20, s20, 0x20000
	s_addc_u32 s21, s21, 0
	global_load_dwordx4 v[142:145], v133, s[20:21] offset:0
	s_waitcnt vmcnt(26)
	v_pk_mul_f32 v[154:155], v[154:155], s[74:75] op_sel_hi:[1,0]
	v_pk_mul_f32 v[156:157], v[156:157], s[74:75] op_sel_hi:[1,0]
	v_pk_fma_f32 v[64:65], v[64:65], 0.5, v[154:155] op_sel_hi:[1,0,1]
	v_pk_fma_f32 v[66:67], v[66:67], 0.5, v[156:157] op_sel_hi:[1,0,1]
	global_store_dwordx4 v133, v[64:67], s[22:23] offset:576
	global_load_dwordx4 v[154:157], v133, s[20:21] offset:64
	s_waitcnt vmcnt(26)
	v_pk_mul_f32 v[158:159], v[158:159], s[74:75] op_sel_hi:[1,0]
	v_pk_mul_f32 v[160:161], v[160:161], s[74:75] op_sel_hi:[1,0]
	v_pk_fma_f32 v[60:61], v[60:61], 0.5, v[158:159] op_sel_hi:[1,0,1]
	v_pk_fma_f32 v[62:63], v[62:63], 0.5, v[160:161] op_sel_hi:[1,0,1]
	s_add_u32 s22, s22, 0xa0000
	s_addc_u32 s23, s23, 0
	global_store_dwordx4 v133, v[60:63], s[22:23] offset:0
	global_load_dwordx4 v[158:161], v133, s[20:21] offset:512
	s_waitcnt vmcnt(26)
	v_pk_mul_f32 v[176:177], v[176:177], s[74:75] op_sel_hi:[1,0]
	v_pk_mul_f32 v[178:179], v[178:179], s[74:75] op_sel_hi:[1,0]
	v_pk_fma_f32 v[56:57], v[56:57], 0.5, v[176:177] op_sel_hi:[1,0,1]
	v_pk_fma_f32 v[58:59], v[58:59], 0.5, v[178:179] op_sel_hi:[1,0,1]
	global_store_dwordx4 v133, v[56:59], s[22:23] offset:64
	global_load_dwordx4 v[176:179], v133, s[20:21] offset:576
	s_waitcnt vmcnt(26)
	v_pk_mul_f32 v[180:181], v[180:181], s[74:75] op_sel_hi:[1,0]
	v_pk_mul_f32 v[182:183], v[182:183], s[74:75] op_sel_hi:[1,0]
	v_pk_fma_f32 v[52:53], v[52:53], 0.5, v[180:181] op_sel_hi:[1,0,1]
	v_pk_fma_f32 v[54:55], v[54:55], 0.5, v[182:183] op_sel_hi:[1,0,1]
	global_store_dwordx4 v133, v[52:55], s[22:23] offset:512
	s_waitcnt vmcnt(25)
	v_pk_mul_f32 v[184:185], v[184:185], s[74:75] op_sel_hi:[1,0]
	v_pk_mul_f32 v[186:187], v[186:187], s[74:75] op_sel_hi:[1,0]
	v_pk_fma_f32 v[48:49], v[48:49], 0.5, v[184:185] op_sel_hi:[1,0,1]
	v_pk_fma_f32 v[50:51], v[50:51], 0.5, v[186:187] op_sel_hi:[1,0,1]
	global_store_dwordx4 v133, v[48:51], s[22:23] offset:576
	s_waitcnt vmcnt(24)
	v_pk_mul_f32 v[188:189], v[188:189], s[74:75] op_sel_hi:[1,0]
	v_pk_mul_f32 v[190:191], v[190:191], s[74:75] op_sel_hi:[1,0]
	v_pk_fma_f32 v[44:45], v[44:45], 0.5, v[188:189] op_sel_hi:[1,0,1]
	v_pk_fma_f32 v[46:47], v[46:47], 0.5, v[190:191] op_sel_hi:[1,0,1]
	s_add_u32 s22, s22, 0x20000
	s_addc_u32 s23, s23, 0
	global_store_dwordx4 v133, v[44:47], s[22:23] offset:0
	s_waitcnt vmcnt(23)
	v_pk_mul_f32 v[192:193], v[192:193], s[74:75] op_sel_hi:[1,0]
	v_pk_mul_f32 v[194:195], v[194:195], s[74:75] op_sel_hi:[1,0]
	v_pk_fma_f32 v[40:41], v[40:41], 0.5, v[192:193] op_sel_hi:[1,0,1]
	v_pk_fma_f32 v[42:43], v[42:43], 0.5, v[194:195] op_sel_hi:[1,0,1]
	global_store_dwordx4 v133, v[40:43], s[22:23] offset:64
	s_waitcnt vmcnt(22)
	v_pk_mul_f32 v[208:209], v[208:209], s[74:75] op_sel_hi:[1,0]
	v_pk_mul_f32 v[210:211], v[210:211], s[74:75] op_sel_hi:[1,0]
	v_pk_fma_f32 v[36:37], v[36:37], 0.5, v[208:209] op_sel_hi:[1,0,1]
	v_pk_fma_f32 v[38:39], v[38:39], 0.5, v[210:211] op_sel_hi:[1,0,1]
	global_store_dwordx4 v133, v[36:39], s[22:23] offset:512
	s_waitcnt vmcnt(21)
	v_pk_mul_f32 v[212:213], v[212:213], s[74:75] op_sel_hi:[1,0]
	v_pk_mul_f32 v[214:215], v[214:215], s[74:75] op_sel_hi:[1,0]
	v_pk_fma_f32 v[32:33], v[32:33], 0.5, v[212:213] op_sel_hi:[1,0,1]
	v_pk_fma_f32 v[34:35], v[34:35], 0.5, v[214:215] op_sel_hi:[1,0,1]
	global_store_dwordx4 v133, v[32:35], s[22:23] offset:576
	s_waitcnt vmcnt(20)
	v_pk_mul_f32 v[216:217], v[216:217], s[74:75] op_sel_hi:[1,0]
	v_pk_mul_f32 v[218:219], v[218:219], s[74:75] op_sel_hi:[1,0]
	v_pk_fma_f32 v[28:29], v[28:29], 0.5, v[216:217] op_sel_hi:[1,0,1]
	v_pk_fma_f32 v[30:31], v[30:31], 0.5, v[218:219] op_sel_hi:[1,0,1]
	s_add_u32 s22, s22, 0x20000
	s_addc_u32 s23, s23, 0
	global_store_dwordx4 v133, v[28:31], s[22:23] offset:0
	s_waitcnt vmcnt(19)
	v_pk_mul_f32 v[220:221], v[220:221], s[74:75] op_sel_hi:[1,0]
	v_pk_mul_f32 v[222:223], v[222:223], s[74:75] op_sel_hi:[1,0]
	v_pk_fma_f32 v[24:25], v[24:25], 0.5, v[220:221] op_sel_hi:[1,0,1]
	v_pk_fma_f32 v[26:27], v[26:27], 0.5, v[222:223] op_sel_hi:[1,0,1]
	global_store_dwordx4 v133, v[24:27], s[22:23] offset:64
	s_waitcnt vmcnt(18)
	v_pk_mul_f32 v[224:225], v[224:225], s[74:75] op_sel_hi:[1,0]
	v_pk_mul_f32 v[226:227], v[226:227], s[74:75] op_sel_hi:[1,0]
	v_pk_fma_f32 v[20:21], v[20:21], 0.5, v[224:225] op_sel_hi:[1,0,1]
	v_pk_fma_f32 v[22:23], v[22:23], 0.5, v[226:227] op_sel_hi:[1,0,1]
	global_store_dwordx4 v133, v[20:23], s[22:23] offset:512
	s_waitcnt vmcnt(17)
	v_pk_mul_f32 v[228:229], v[228:229], s[74:75] op_sel_hi:[1,0]
	v_pk_mul_f32 v[230:231], v[230:231], s[74:75] op_sel_hi:[1,0]
	v_pk_fma_f32 v[16:17], v[16:17], 0.5, v[228:229] op_sel_hi:[1,0,1]
	v_pk_fma_f32 v[18:19], v[18:19], 0.5, v[230:231] op_sel_hi:[1,0,1]
	global_store_dwordx4 v133, v[16:19], s[22:23] offset:576
	s_waitcnt vmcnt(16)
	v_pk_mul_f32 v[142:143], v[142:143], s[74:75] op_sel_hi:[1,0]
	v_pk_mul_f32 v[144:145], v[144:145], s[74:75] op_sel_hi:[1,0]
	v_pk_fma_f32 v[12:13], v[12:13], 0.5, v[142:143] op_sel_hi:[1,0,1]
	v_pk_fma_f32 v[14:15], v[14:15], 0.5, v[144:145] op_sel_hi:[1,0,1]
	s_add_u32 s22, s22, 0x20000
	s_addc_u32 s23, s23, 0
	global_store_dwordx4 v133, v[12:15], s[22:23] offset:0
	s_waitcnt vmcnt(15)
	v_pk_mul_f32 v[154:155], v[154:155], s[74:75] op_sel_hi:[1,0]
	v_pk_mul_f32 v[156:157], v[156:157], s[74:75] op_sel_hi:[1,0]
	v_pk_fma_f32 v[8:9], v[8:9], 0.5, v[154:155] op_sel_hi:[1,0,1]
	v_pk_fma_f32 v[10:11], v[10:11], 0.5, v[156:157] op_sel_hi:[1,0,1]
	global_store_dwordx4 v133, v[8:11], s[22:23] offset:64
	s_waitcnt vmcnt(14)
	v_pk_mul_f32 v[158:159], v[158:159], s[74:75] op_sel_hi:[1,0]
	v_pk_mul_f32 v[160:161], v[160:161], s[74:75] op_sel_hi:[1,0]
	v_pk_fma_f32 v[4:5], v[4:5], 0.5, v[158:159] op_sel_hi:[1,0,1]
	v_pk_fma_f32 v[6:7], v[6:7], 0.5, v[160:161] op_sel_hi:[1,0,1]
	global_store_dwordx4 v133, v[4:7], s[22:23] offset:512
	s_waitcnt vmcnt(13)
	v_pk_mul_f32 v[176:177], v[176:177], s[74:75] op_sel_hi:[1,0]
	v_pk_mul_f32 v[178:179], v[178:179], s[74:75] op_sel_hi:[1,0]
	v_pk_fma_f32 v[0:1], v[0:1], 0.5, v[176:177] op_sel_hi:[1,0,1]
	v_pk_fma_f32 v[2:3], v[2:3], 0.5, v[178:179] op_sel_hi:[1,0,1]
	global_store_dwordx4 v133, v[0:3], s[22:23] offset:576
	s_branch .Le484_join
